# u-side of PEER gather rewritten by hand: coalesced 128B row gathers + LDS transpose to MFMA A layout + register accumulation instead of LDS RMW; expert-id loads batched
# speedup vs baseline: 1.1014x; 1.1014x over previous
.LBB0_1973:
	v_readfirstlane_b32 s8, v70
	s_mul_i32 s9, s30, 11
	s_add_i32 s8, s8, s9
	s_cmp_lg_u64 exec, -1
	s_cbranch_scc1 .Lu_fallback
	s_cmp_lt_i32 s8, s29
	s_cbranch_scc1 .Lu_new

.Lu_new:
	v_and_b32_e32 v208, 63, v179
	v_lshrrev_b32_e32 v102, 6, v179
	v_and_b32_e32 v209, 15, v179
	v_readfirstlane_b32 s20, v72
	v_readfirstlane_b32 s21, v73
	v_readfirstlane_b32 s50, v74
	v_readfirstlane_b32 s51, v75
	v_readfirstlane_b32 s52, v76
	v_readfirstlane_b32 s53, v77
	s_lshl_b32 s80, s30, 10
	s_mul_i32 s81, s80, 11
	s_sub_i32 s81, 0x80, s81
	v_lshlrev_b32_e32 v0, 9, v70
	v_lshl_add_u32 v0, v208, 2, v0
	s_lshl_b32 s8, s30, 9
	global_load_dword v2, v0, s[20:21]
	global_load_dword v3, v0, s[20:21] offset:256
	v_add_u32_e32 v0, s8, v0
	global_load_dword v4, v0, s[20:21]
	global_load_dword v5, v0, s[20:21] offset:256
	v_add_u32_e32 v0, s8, v0
	global_load_dword v6, v0, s[20:21]
	global_load_dword v7, v0, s[20:21] offset:256
	v_add_u32_e32 v0, s8, v0
	global_load_dword v8, v0, s[20:21]
	global_load_dword v9, v0, s[20:21] offset:256
	v_add_u32_e32 v0, s8, v0
	global_load_dword v10, v0, s[20:21]
	global_load_dword v11, v0, s[20:21] offset:256
	v_add_u32_e32 v0, s8, v0
	global_load_dword v12, v0, s[20:21]
	global_load_dword v13, v0, s[20:21] offset:256
	v_add_u32_e32 v0, s8, v0
	global_load_dword v14, v0, s[20:21]
	global_load_dword v15, v0, s[20:21] offset:256
	v_add_u32_e32 v0, s8, v0
	global_load_dword v16, v0, s[20:21]
	global_load_dword v17, v0, s[20:21] offset:256
	v_add_u32_e32 v0, s8, v0
	global_load_dword v18, v0, s[20:21]
	global_load_dword v19, v0, s[20:21] offset:256
	v_add_u32_e32 v0, s8, v0
	global_load_dword v20, v0, s[20:21]
	global_load_dword v21, v0, s[20:21] offset:256
	v_add_u32_e32 v0, s8, v0
	global_load_dword v22, v0, s[20:21]
	global_load_dword v23, v0, s[20:21] offset:256
	v_add_u32_e32 v0, s8, v0
	global_load_dword v24, v0, s[20:21]
	global_load_dword v25, v0, s[20:21] offset:256
	v_and_b32_e32 v71, 1, v209
	v_cmp_ne_u32_e64 s[54:55], 0, v71
	v_bfe_u32 v71, v209, 1, 1
	v_cmp_ne_u32_e64 s[56:57], 0, v71
	v_bfe_u32 v71, v209, 2, 1
	v_cmp_ne_u32_e64 s[58:59], 0, v71
	v_bfe_u32 v71, v209, 3, 1
	v_cmp_ne_u32_e64 s[60:61], 0, v71
	v_mul_u32_u24_e32 v172, 0x3000, v102
	v_lshlrev_b32_e32 v168, 11, v102
	v_add_u32_e32 v168, 49152, v168
	v_lshrrev_b32_e32 v71, 1, v209
	v_lshlrev_b32_e32 v71, 4, v71
	v_lshl_add_u32 v71, v103, 2, v71
	v_and_b32_e32 v93, 1, v209
	v_lshl_add_u32 v71, v93, 1, v71
	v_lshl_add_u32 v173, v71, 2, v172
	v_add_u32_e32 v173, 6144, v173
	v_lshrrev_b32_e32 v174, 2, v209
	v_lshrrev_b32_e32 v175, 3, v209
	v_xor_b32_e32 v174, v174, v175
	v_and_b32_e32 v174, 1, v174
	v_lshlrev_b32_e32 v174, 1, v174
	v_lshrrev_b32_e32 v175, 1, v209
	v_xor_b32_e32 v93, v174, v175
	v_lshlrev_b32_e32 v71, 1, v103
	v_xor_b32_e32 v71, v71, v93
	v_lshl_add_u32 v71, v209, 3, v71
	v_lshl_add_u32 v169, v71, 4, v168
	v_xor_b32_e32 v170, 16, v169
	v_lshrrev_b32_e32 v176, 3, v208
	v_and_b32_e32 v177, 7, v208
	v_lshrrev_b32_e32 v174, 2, v176
	v_lshrrev_b32_e32 v175, 3, v176
	v_xor_b32_e32 v174, v174, v175
	v_and_b32_e32 v174, 1, v174
	v_lshlrev_b32_e32 v174, 1, v174
	v_lshrrev_b32_e32 v175, 1, v176
	v_xor_b32_e32 v93, v174, v175
	v_xor_b32_e32 v93, v93, v177
	v_lshlrev_b32_e32 v166, 4, v93
	v_add_u32_e32 v71, 8, v176
	v_lshrrev_b32_e32 v174, 2, v71
	v_lshrrev_b32_e32 v175, 3, v71
	v_xor_b32_e32 v174, v174, v175
	v_and_b32_e32 v174, 1, v174
	v_lshlrev_b32_e32 v174, 1, v174
	v_lshrrev_b32_e32 v175, 1, v71
	v_xor_b32_e32 v93, v174, v175
	v_xor_b32_e32 v93, v93, v177
	v_lshlrev_b32_e32 v167, 4, v93
	v_lshl_add_u32 v172, v176, 2, v172
	v_lshl_add_u32 v168, v208, 4, v168
	v_lshlrev_b32_e32 v171, 10, v70
	v_lshl_add_u32 v171, v103, 5, v171
	v_mov_b32_e32 v242, 0
	v_mov_b32_e32 v243, 0
	v_mov_b32_e32 v244, 0
	v_mov_b32_e32 v245, 0
	v_mov_b32_e32 v246, 0
	v_mov_b32_e32 v247, 0
	v_mov_b32_e32 v248, 0
	v_mov_b32_e32 v249, 0
	v_mov_b32_e32 v238, 0
	v_mov_b32_e32 v239, 0
	v_mov_b32_e32 v240, 0
	v_mov_b32_e32 v241, 0
	v_mov_b32_e32 v94, 0
	v_mov_b32_e32 v95, 0
	v_mov_b32_e32 v96, 0
	v_mov_b32_e32 v97, 0
	v_mov_b32_e32 v98, 0
	v_mov_b32_e32 v99, 0
	v_mov_b32_e32 v100, 0
	v_mov_b32_e32 v101, 0
	v_mov_b32_e32 v66, 0
	v_mov_b32_e32 v67, 0
	v_mov_b32_e32 v68, 0
	v_mov_b32_e32 v69, 0
	global_load_dwordx4 v[134:137], v171, s[52:53]
	global_load_dwordx4 v[138:141], v171, s[52:53] offset:16
	s_waitcnt vmcnt(24)
	ds_write2st64_b32 v109, v2, v3 offset0:0 offset1:1
	s_waitcnt vmcnt(22)
	ds_write2st64_b32 v109, v4, v5 offset0:2 offset1:3
	s_waitcnt vmcnt(20)
	ds_write2st64_b32 v109, v6, v7 offset0:4 offset1:5
	s_waitcnt vmcnt(18)
	ds_write2st64_b32 v109, v8, v9 offset0:6 offset1:7
	s_waitcnt vmcnt(16)
	ds_write2st64_b32 v109, v10, v11 offset0:8 offset1:9
	s_waitcnt vmcnt(14)
	ds_write2st64_b32 v109, v12, v13 offset0:10 offset1:11
	s_waitcnt vmcnt(12)
	ds_write2st64_b32 v109, v14, v15 offset0:12 offset1:13
	s_waitcnt vmcnt(10)
	ds_write2st64_b32 v109, v16, v17 offset0:14 offset1:15
	s_waitcnt vmcnt(8)
	ds_write2st64_b32 v109, v18, v19 offset0:16 offset1:17
	s_waitcnt vmcnt(6)
	ds_write2st64_b32 v109, v20, v21 offset0:18 offset1:19
	s_waitcnt vmcnt(4)
	ds_write2st64_b32 v109, v22, v23 offset0:20 offset1:21
	s_waitcnt vmcnt(2)
	ds_write2st64_b32 v109, v24, v25 offset0:22 offset1:23
	v_add_u32_e32 v0, 0, v172
	ds_read2_b32 v[150:151], v0 offset0:0 offset1:8
	ds_read2_b32 v[152:153], v0 offset0:16 offset1:24
	ds_read2_b32 v[154:155], v0 offset0:32 offset1:40
	ds_read2_b32 v[156:157], v0 offset0:48 offset1:56
	ds_read2_b32 v[158:159], v0 offset0:64 offset1:72
	ds_read2_b32 v[160:161], v0 offset0:80 offset1:88
	ds_read2_b32 v[162:163], v0 offset0:96 offset1:104
	ds_read2_b32 v[164:165], v0 offset0:112 offset1:120
	s_waitcnt lgkmcnt(0)
	v_lshl_add_u32 v174, v150, 10, v166
	global_load_dwordx4 v[2:5], v174, s[50:51]
	v_lshl_add_u32 v175, v151, 10, v167
	global_load_dwordx4 v[6:9], v175, s[50:51]
	v_lshl_add_u32 v176, v152, 10, v166
	global_load_dwordx4 v[10:13], v176, s[50:51]
	v_lshl_add_u32 v177, v153, 10, v167
	global_load_dwordx4 v[14:17], v177, s[50:51]
	v_lshl_add_u32 v174, v154, 10, v166
	global_load_dwordx4 v[18:21], v174, s[50:51]
	v_lshl_add_u32 v175, v155, 10, v167
	global_load_dwordx4 v[22:25], v175, s[50:51]
	v_lshl_add_u32 v176, v156, 10, v166
	global_load_dwordx4 v[26:29], v176, s[50:51]
	v_lshl_add_u32 v177, v157, 10, v167
	global_load_dwordx4 v[30:33], v177, s[50:51]
	v_lshl_add_u32 v174, v158, 10, v166
	global_load_dwordx4 v[34:37], v174, s[50:51]
	v_lshl_add_u32 v175, v159, 10, v167
	global_load_dwordx4 v[38:41], v175, s[50:51]
	v_lshl_add_u32 v176, v160, 10, v166
	global_load_dwordx4 v[42:45], v176, s[50:51]
	v_lshl_add_u32 v177, v161, 10, v167
	global_load_dwordx4 v[46:49], v177, s[50:51]
	v_lshl_add_u32 v174, v162, 10, v166
	global_load_dwordx4 v[50:53], v174, s[50:51]
	v_lshl_add_u32 v175, v163, 10, v167
	global_load_dwordx4 v[54:57], v175, s[50:51]
	v_lshl_add_u32 v176, v164, 10, v166
	global_load_dwordx4 v[58:61], v176, s[50:51]
	v_lshl_add_u32 v177, v165, 10, v167
	global_load_dwordx4 v[62:65], v177, s[50:51]
	v_add_u32_e32 v0, 512, v172
	ds_read2_b32 v[150:151], v0 offset0:0 offset1:8
	ds_read2_b32 v[152:153], v0 offset0:16 offset1:24
	ds_read2_b32 v[154:155], v0 offset0:32 offset1:40
	ds_read2_b32 v[156:157], v0 offset0:48 offset1:56
	ds_read2_b32 v[158:159], v0 offset0:64 offset1:72
	ds_read2_b32 v[160:161], v0 offset0:80 offset1:88
	ds_read2_b32 v[162:163], v0 offset0:96 offset1:104
	ds_read2_b32 v[164:165], v0 offset0:112 offset1:120
	v_add_u32_e32 v171, s80, v171
	global_load_dwordx4 v[142:145], v171, s[52:53]
	global_load_dwordx4 v[146:149], v171, s[52:53] offset:16
	s_mov_b32 s49, 0
.Lu_cloop:
	s_waitcnt vmcnt(16)
	ds_write_b128 v168, v[2:5]
	ds_write_b128 v168, v[6:9] offset:1024
	s_waitcnt lgkmcnt(2)
	v_lshl_add_u32 v174, v150, 10, v166
	global_load_dwordx4 v[2:5], v174, s[50:51]
	v_lshl_add_u32 v175, v151, 10, v167
	global_load_dwordx4 v[6:9], v175, s[50:51]
	ds_read_b128 v[180:183], v169
	ds_read_b128 v[184:187], v170
	s_waitcnt vmcnt(16)
	ds_write_b128 v168, v[10:13]
	ds_write_b128 v168, v[14:17] offset:1024
	v_lshl_add_u32 v176, v152, 10, v166
	global_load_dwordx4 v[10:13], v176, s[50:51]
	v_lshl_add_u32 v177, v153, 10, v167
	global_load_dwordx4 v[14:17], v177, s[50:51]
	ds_read_b128 v[188:191], v169
	ds_read_b128 v[192:195], v170
	s_waitcnt lgkmcnt(4)
	v_mfma_f32_16x16x32_fp8_fp8 v[196:199], v[180:181], v[134:135], 0
	v_mfma_f32_16x16x32_fp8_fp8 v[196:199], v[182:183], v[136:137], v[196:199]
	v_mfma_f32_16x16x32_fp8_fp8 v[196:199], v[184:185], v[138:139], v[196:199]
	v_mfma_f32_16x16x32_fp8_fp8 v[196:199], v[186:187], v[140:141], v[196:199]
	s_waitcnt vmcnt(16)
	ds_write_b128 v168, v[18:21]
	ds_write_b128 v168, v[22:25] offset:1024
	v_lshl_add_u32 v174, v154, 10, v166
	global_load_dwordx4 v[18:21], v174, s[50:51]
	v_lshl_add_u32 v175, v155, 10, v167
	global_load_dwordx4 v[22:25], v175, s[50:51]
	ds_read_b128 v[180:183], v169
	ds_read_b128 v[184:187], v170
	s_waitcnt lgkmcnt(4)
	v_mfma_f32_16x16x32_fp8_fp8 v[200:203], v[188:189], v[134:135], 0
	v_mfma_f32_16x16x32_fp8_fp8 v[200:203], v[190:191], v[136:137], v[200:203]
	v_mfma_f32_16x16x32_fp8_fp8 v[200:203], v[192:193], v[138:139], v[200:203]
	v_mfma_f32_16x16x32_fp8_fp8 v[200:203], v[194:195], v[140:141], v[200:203]
	v_cndmask_b32_e64 v226, v196, v198, s[54:55]
	v_cndmask_b32_e64 v227, v197, v199, s[54:55]
	s_waitcnt vmcnt(16)
	ds_write_b128 v168, v[26:29]
	ds_write_b128 v168, v[30:33] offset:1024
	v_lshl_add_u32 v176, v156, 10, v166
	global_load_dwordx4 v[26:29], v176, s[50:51]
	v_lshl_add_u32 v177, v157, 10, v167
	global_load_dwordx4 v[30:33], v177, s[50:51]
	ds_read_b128 v[188:191], v169
	ds_read_b128 v[192:195], v170
	s_waitcnt lgkmcnt(4)
	v_mfma_f32_16x16x32_fp8_fp8 v[204:207], v[180:181], v[134:135], 0
	v_mfma_f32_16x16x32_fp8_fp8 v[204:207], v[182:183], v[136:137], v[204:207]
	v_mfma_f32_16x16x32_fp8_fp8 v[204:207], v[184:185], v[138:139], v[204:207]
	v_mfma_f32_16x16x32_fp8_fp8 v[204:207], v[186:187], v[140:141], v[204:207]
	v_cndmask_b32_e64 v228, v200, v202, s[54:55]
	v_cndmask_b32_e64 v229, v201, v203, s[54:55]
	v_cndmask_b32_e64 v230, v226, v228, s[56:57]
	v_cndmask_b32_e64 v231, v227, v229, s[56:57]
	s_waitcnt vmcnt(16)
	ds_write_b128 v168, v[34:37]
	ds_write_b128 v168, v[38:41] offset:1024
	v_lshl_add_u32 v174, v158, 10, v166
	global_load_dwordx4 v[34:37], v174, s[50:51]
	v_lshl_add_u32 v175, v159, 10, v167
	global_load_dwordx4 v[38:41], v175, s[50:51]
	ds_read_b128 v[180:183], v169
	ds_read_b128 v[184:187], v170
	s_waitcnt lgkmcnt(4)
	v_mfma_f32_16x16x32_fp8_fp8 v[216:219], v[188:189], v[134:135], 0
	v_mfma_f32_16x16x32_fp8_fp8 v[216:219], v[190:191], v[136:137], v[216:219]
	v_mfma_f32_16x16x32_fp8_fp8 v[216:219], v[192:193], v[138:139], v[216:219]
	v_mfma_f32_16x16x32_fp8_fp8 v[216:219], v[194:195], v[140:141], v[216:219]
	v_cndmask_b32_e64 v226, v204, v206, s[54:55]
	v_cndmask_b32_e64 v227, v205, v207, s[54:55]
	s_waitcnt vmcnt(16)
	ds_write_b128 v168, v[42:45]
	ds_write_b128 v168, v[46:49] offset:1024
	v_lshl_add_u32 v176, v160, 10, v166
	global_load_dwordx4 v[42:45], v176, s[50:51]
	v_lshl_add_u32 v177, v161, 10, v167
	global_load_dwordx4 v[46:49], v177, s[50:51]
	ds_read_b128 v[188:191], v169
	ds_read_b128 v[192:195], v170
	s_waitcnt lgkmcnt(4)
	v_mfma_f32_16x16x32_fp8_fp8 v[196:199], v[180:181], v[134:135], 0
	v_mfma_f32_16x16x32_fp8_fp8 v[196:199], v[182:183], v[136:137], v[196:199]
	v_mfma_f32_16x16x32_fp8_fp8 v[196:199], v[184:185], v[138:139], v[196:199]
	v_mfma_f32_16x16x32_fp8_fp8 v[196:199], v[186:187], v[140:141], v[196:199]
	v_cndmask_b32_e64 v228, v216, v218, s[54:55]
	v_cndmask_b32_e64 v229, v217, v219, s[54:55]
	v_cndmask_b32_e64 v232, v226, v228, s[56:57]
	v_cndmask_b32_e64 v233, v227, v229, s[56:57]
	s_waitcnt vmcnt(16)
	ds_write_b128 v168, v[50:53]
	ds_write_b128 v168, v[54:57] offset:1024
	v_lshl_add_u32 v174, v162, 10, v166
	global_load_dwordx4 v[50:53], v174, s[50:51]
	v_lshl_add_u32 v175, v163, 10, v167
	global_load_dwordx4 v[54:57], v175, s[50:51]
	ds_read_b128 v[180:183], v169
	ds_read_b128 v[184:187], v170
	s_waitcnt lgkmcnt(4)
	v_mfma_f32_16x16x32_fp8_fp8 v[200:203], v[188:189], v[134:135], 0
	v_mfma_f32_16x16x32_fp8_fp8 v[200:203], v[190:191], v[136:137], v[200:203]
	v_mfma_f32_16x16x32_fp8_fp8 v[200:203], v[192:193], v[138:139], v[200:203]
	v_mfma_f32_16x16x32_fp8_fp8 v[200:203], v[194:195], v[140:141], v[200:203]
	v_cndmask_b32_e64 v226, v196, v198, s[54:55]
	v_cndmask_b32_e64 v227, v197, v199, s[54:55]
	s_waitcnt vmcnt(16)
	ds_write_b128 v168, v[58:61]
	ds_write_b128 v168, v[62:65] offset:1024
	v_lshl_add_u32 v176, v164, 10, v166
	global_load_dwordx4 v[58:61], v176, s[50:51]
	v_lshl_add_u32 v177, v165, 10, v167
	global_load_dwordx4 v[62:65], v177, s[50:51]
	ds_read_b128 v[188:191], v169
	ds_read_b128 v[192:195], v170
	s_waitcnt lgkmcnt(4)
	v_mfma_f32_16x16x32_fp8_fp8 v[204:207], v[180:181], v[134:135], 0
	v_mfma_f32_16x16x32_fp8_fp8 v[204:207], v[182:183], v[136:137], v[204:207]
	v_mfma_f32_16x16x32_fp8_fp8 v[204:207], v[184:185], v[138:139], v[204:207]
	v_mfma_f32_16x16x32_fp8_fp8 v[204:207], v[186:187], v[140:141], v[204:207]
	v_cndmask_b32_e64 v228, v200, v202, s[54:55]
	v_cndmask_b32_e64 v229, v201, v203, s[54:55]
	v_cndmask_b32_e64 v234, v226, v228, s[56:57]
	v_cndmask_b32_e64 v235, v227, v229, s[56:57]
	s_waitcnt lgkmcnt(0)
	v_mfma_f32_16x16x32_fp8_fp8 v[216:219], v[188:189], v[134:135], 0
	v_mfma_f32_16x16x32_fp8_fp8 v[216:219], v[190:191], v[136:137], v[216:219]
	v_mfma_f32_16x16x32_fp8_fp8 v[216:219], v[192:193], v[138:139], v[216:219]
	v_mfma_f32_16x16x32_fp8_fp8 v[216:219], v[194:195], v[140:141], v[216:219]
	v_add_u32_e32 v0, 1024, v172
	ds_read2_b32 v[150:151], v0 offset0:0 offset1:8
	ds_read2_b32 v[152:153], v0 offset0:16 offset1:24
	ds_read2_b32 v[154:155], v0 offset0:32 offset1:40
	ds_read2_b32 v[156:157], v0 offset0:48 offset1:56
	ds_read2_b32 v[158:159], v0 offset0:64 offset1:72
	ds_read2_b32 v[160:161], v0 offset0:80 offset1:88
	ds_read2_b32 v[162:163], v0 offset0:96 offset1:104
	ds_read2_b32 v[164:165], v0 offset0:112 offset1:120
	v_add_u32_e32 v171, s80, v171
	global_load_dwordx4 v[134:137], v171, s[52:53]
	global_load_dwordx4 v[138:141], v171, s[52:53] offset:16
	v_cndmask_b32_e64 v226, v204, v206, s[54:55]
	v_cndmask_b32_e64 v227, v205, v207, s[54:55]
	v_cndmask_b32_e64 v228, v216, v218, s[54:55]
	v_cndmask_b32_e64 v229, v217, v219, s[54:55]
	v_cndmask_b32_e64 v236, v226, v228, s[56:57]
	v_cndmask_b32_e64 v237, v227, v229, s[56:57]
	v_cndmask_b32_e64 v226, v230, v232, s[58:59]
	v_cndmask_b32_e64 v228, v234, v236, s[58:59]
	v_cndmask_b32_e64 v227, v231, v233, s[58:59]
	v_cndmask_b32_e64 v229, v235, v237, s[58:59]
	v_cndmask_b32_e64 v226, v226, v228, s[60:61]
	v_cndmask_b32_e64 v227, v227, v229, s[60:61]
	v_add_f32_e32 v242, v242, v226
	v_add_f32_e32 v243, v243, v227
	s_waitcnt vmcnt(16)
	ds_write_b128 v168, v[2:5]
	ds_write_b128 v168, v[6:9] offset:1024
	s_waitcnt lgkmcnt(2)
	v_lshl_add_u32 v174, v150, 10, v166
	global_load_dwordx4 v[2:5], v174, s[50:51]
	v_lshl_add_u32 v175, v151, 10, v167
	global_load_dwordx4 v[6:9], v175, s[50:51]
	ds_read_b128 v[180:183], v169
	ds_read_b128 v[184:187], v170
	s_waitcnt vmcnt(16)
	ds_write_b128 v168, v[10:13]
	ds_write_b128 v168, v[14:17] offset:1024
	v_lshl_add_u32 v176, v152, 10, v166
	global_load_dwordx4 v[10:13], v176, s[50:51]
	v_lshl_add_u32 v177, v153, 10, v167
	global_load_dwordx4 v[14:17], v177, s[50:51]
	ds_read_b128 v[188:191], v169
	ds_read_b128 v[192:195], v170
	s_waitcnt lgkmcnt(4)
	v_mfma_f32_16x16x32_fp8_fp8 v[196:199], v[180:181], v[142:143], 0
	v_mfma_f32_16x16x32_fp8_fp8 v[196:199], v[182:183], v[144:145], v[196:199]
	v_mfma_f32_16x16x32_fp8_fp8 v[196:199], v[184:185], v[146:147], v[196:199]
	v_mfma_f32_16x16x32_fp8_fp8 v[196:199], v[186:187], v[148:149], v[196:199]
	s_waitcnt vmcnt(16)
	ds_write_b128 v168, v[18:21]
	ds_write_b128 v168, v[22:25] offset:1024
	v_lshl_add_u32 v174, v154, 10, v166
	global_load_dwordx4 v[18:21], v174, s[50:51]
	v_lshl_add_u32 v175, v155, 10, v167
	global_load_dwordx4 v[22:25], v175, s[50:51]
	ds_read_b128 v[180:183], v169
	ds_read_b128 v[184:187], v170
	s_waitcnt lgkmcnt(4)
	v_mfma_f32_16x16x32_fp8_fp8 v[200:203], v[188:189], v[142:143], 0
	v_mfma_f32_16x16x32_fp8_fp8 v[200:203], v[190:191], v[144:145], v[200:203]
	v_mfma_f32_16x16x32_fp8_fp8 v[200:203], v[192:193], v[146:147], v[200:203]
	v_mfma_f32_16x16x32_fp8_fp8 v[200:203], v[194:195], v[148:149], v[200:203]
	v_cndmask_b32_e64 v226, v196, v198, s[54:55]
	v_cndmask_b32_e64 v227, v197, v199, s[54:55]
	s_waitcnt vmcnt(16)
	ds_write_b128 v168, v[26:29]
	ds_write_b128 v168, v[30:33] offset:1024
	v_lshl_add_u32 v176, v156, 10, v166
	global_load_dwordx4 v[26:29], v176, s[50:51]
	v_lshl_add_u32 v177, v157, 10, v167
	global_load_dwordx4 v[30:33], v177, s[50:51]
	ds_read_b128 v[188:191], v169
	ds_read_b128 v[192:195], v170
	s_waitcnt lgkmcnt(4)
	v_mfma_f32_16x16x32_fp8_fp8 v[204:207], v[180:181], v[142:143], 0
	v_mfma_f32_16x16x32_fp8_fp8 v[204:207], v[182:183], v[144:145], v[204:207]
	v_mfma_f32_16x16x32_fp8_fp8 v[204:207], v[184:185], v[146:147], v[204:207]
	v_mfma_f32_16x16x32_fp8_fp8 v[204:207], v[186:187], v[148:149], v[204:207]
	v_cndmask_b32_e64 v228, v200, v202, s[54:55]
	v_cndmask_b32_e64 v229, v201, v203, s[54:55]
	v_cndmask_b32_e64 v230, v226, v228, s[56:57]
	v_cndmask_b32_e64 v231, v227, v229, s[56:57]
	s_waitcnt vmcnt(16)
	ds_write_b128 v168, v[34:37]
	ds_write_b128 v168, v[38:41] offset:1024
	v_lshl_add_u32 v174, v158, 10, v166
	global_load_dwordx4 v[34:37], v174, s[50:51]
	v_lshl_add_u32 v175, v159, 10, v167
	global_load_dwordx4 v[38:41], v175, s[50:51]
	ds_read_b128 v[180:183], v169
	ds_read_b128 v[184:187], v170
	s_waitcnt lgkmcnt(4)
	v_mfma_f32_16x16x32_fp8_fp8 v[216:219], v[188:189], v[142:143], 0
	v_mfma_f32_16x16x32_fp8_fp8 v[216:219], v[190:191], v[144:145], v[216:219]
	v_mfma_f32_16x16x32_fp8_fp8 v[216:219], v[192:193], v[146:147], v[216:219]
	v_mfma_f32_16x16x32_fp8_fp8 v[216:219], v[194:195], v[148:149], v[216:219]
	v_cndmask_b32_e64 v226, v204, v206, s[54:55]
	v_cndmask_b32_e64 v227, v205, v207, s[54:55]
	s_waitcnt vmcnt(16)
	ds_write_b128 v168, v[42:45]
	ds_write_b128 v168, v[46:49] offset:1024
	v_lshl_add_u32 v176, v160, 10, v166
	global_load_dwordx4 v[42:45], v176, s[50:51]
	v_lshl_add_u32 v177, v161, 10, v167
	global_load_dwordx4 v[46:49], v177, s[50:51]
	ds_read_b128 v[188:191], v169
	ds_read_b128 v[192:195], v170
	s_waitcnt lgkmcnt(4)
	v_mfma_f32_16x16x32_fp8_fp8 v[196:199], v[180:181], v[142:143], 0
	v_mfma_f32_16x16x32_fp8_fp8 v[196:199], v[182:183], v[144:145], v[196:199]
	v_mfma_f32_16x16x32_fp8_fp8 v[196:199], v[184:185], v[146:147], v[196:199]
	v_mfma_f32_16x16x32_fp8_fp8 v[196:199], v[186:187], v[148:149], v[196:199]
	v_cndmask_b32_e64 v228, v216, v218, s[54:55]
	v_cndmask_b32_e64 v229, v217, v219, s[54:55]
	v_cndmask_b32_e64 v232, v226, v228, s[56:57]
	v_cndmask_b32_e64 v233, v227, v229, s[56:57]
	s_waitcnt vmcnt(16)
	ds_write_b128 v168, v[50:53]
	ds_write_b128 v168, v[54:57] offset:1024
	v_lshl_add_u32 v174, v162, 10, v166
	global_load_dwordx4 v[50:53], v174, s[50:51]
	v_lshl_add_u32 v175, v163, 10, v167
	global_load_dwordx4 v[54:57], v175, s[50:51]
	ds_read_b128 v[180:183], v169
	ds_read_b128 v[184:187], v170
	s_waitcnt lgkmcnt(4)
	v_mfma_f32_16x16x32_fp8_fp8 v[200:203], v[188:189], v[142:143], 0
	v_mfma_f32_16x16x32_fp8_fp8 v[200:203], v[190:191], v[144:145], v[200:203]
	v_mfma_f32_16x16x32_fp8_fp8 v[200:203], v[192:193], v[146:147], v[200:203]
	v_mfma_f32_16x16x32_fp8_fp8 v[200:203], v[194:195], v[148:149], v[200:203]
	v_cndmask_b32_e64 v226, v196, v198, s[54:55]
	v_cndmask_b32_e64 v227, v197, v199, s[54:55]
	s_waitcnt vmcnt(16)
	ds_write_b128 v168, v[58:61]
	ds_write_b128 v168, v[62:65] offset:1024
	v_lshl_add_u32 v176, v164, 10, v166
	global_load_dwordx4 v[58:61], v176, s[50:51]
	v_lshl_add_u32 v177, v165, 10, v167
	global_load_dwordx4 v[62:65], v177, s[50:51]
	ds_read_b128 v[188:191], v169
	ds_read_b128 v[192:195], v170
	s_waitcnt lgkmcnt(4)
	v_mfma_f32_16x16x32_fp8_fp8 v[204:207], v[180:181], v[142:143], 0
	v_mfma_f32_16x16x32_fp8_fp8 v[204:207], v[182:183], v[144:145], v[204:207]
	v_mfma_f32_16x16x32_fp8_fp8 v[204:207], v[184:185], v[146:147], v[204:207]
	v_mfma_f32_16x16x32_fp8_fp8 v[204:207], v[186:187], v[148:149], v[204:207]
	v_cndmask_b32_e64 v228, v200, v202, s[54:55]
	v_cndmask_b32_e64 v229, v201, v203, s[54:55]
	v_cndmask_b32_e64 v234, v226, v228, s[56:57]
	v_cndmask_b32_e64 v235, v227, v229, s[56:57]
	s_waitcnt lgkmcnt(0)
	v_mfma_f32_16x16x32_fp8_fp8 v[216:219], v[188:189], v[142:143], 0
	v_mfma_f32_16x16x32_fp8_fp8 v[216:219], v[190:191], v[144:145], v[216:219]
	v_mfma_f32_16x16x32_fp8_fp8 v[216:219], v[192:193], v[146:147], v[216:219]
	v_mfma_f32_16x16x32_fp8_fp8 v[216:219], v[194:195], v[148:149], v[216:219]
	v_add_u32_e32 v0, 1536, v172
	ds_read2_b32 v[150:151], v0 offset0:0 offset1:8
	ds_read2_b32 v[152:153], v0 offset0:16 offset1:24
	ds_read2_b32 v[154:155], v0 offset0:32 offset1:40
	ds_read2_b32 v[156:157], v0 offset0:48 offset1:56
	ds_read2_b32 v[158:159], v0 offset0:64 offset1:72
	ds_read2_b32 v[160:161], v0 offset0:80 offset1:88
	ds_read2_b32 v[162:163], v0 offset0:96 offset1:104
	ds_read2_b32 v[164:165], v0 offset0:112 offset1:120
	v_add_u32_e32 v171, s80, v171
	global_load_dwordx4 v[142:145], v171, s[52:53]
	global_load_dwordx4 v[146:149], v171, s[52:53] offset:16
	v_cndmask_b32_e64 v226, v204, v206, s[54:55]
	v_cndmask_b32_e64 v227, v205, v207, s[54:55]
	v_cndmask_b32_e64 v228, v216, v218, s[54:55]
	v_cndmask_b32_e64 v229, v217, v219, s[54:55]
	v_cndmask_b32_e64 v236, v226, v228, s[56:57]
	v_cndmask_b32_e64 v237, v227, v229, s[56:57]
	v_cndmask_b32_e64 v226, v230, v232, s[58:59]
	v_cndmask_b32_e64 v228, v234, v236, s[58:59]
	v_cndmask_b32_e64 v227, v231, v233, s[58:59]
	v_cndmask_b32_e64 v229, v235, v237, s[58:59]
	v_cndmask_b32_e64 v226, v226, v228, s[60:61]
	v_cndmask_b32_e64 v227, v227, v229, s[60:61]
	v_add_f32_e32 v244, v244, v226
	v_add_f32_e32 v245, v245, v227
	s_waitcnt vmcnt(16)
	ds_write_b128 v168, v[2:5]
	ds_write_b128 v168, v[6:9] offset:1024
	s_waitcnt lgkmcnt(2)
	v_lshl_add_u32 v174, v150, 10, v166
	global_load_dwordx4 v[2:5], v174, s[50:51]
	v_lshl_add_u32 v175, v151, 10, v167
	global_load_dwordx4 v[6:9], v175, s[50:51]
	ds_read_b128 v[180:183], v169
	ds_read_b128 v[184:187], v170
	s_waitcnt vmcnt(16)
	ds_write_b128 v168, v[10:13]
	ds_write_b128 v168, v[14:17] offset:1024
	v_lshl_add_u32 v176, v152, 10, v166
	global_load_dwordx4 v[10:13], v176, s[50:51]
	v_lshl_add_u32 v177, v153, 10, v167
	global_load_dwordx4 v[14:17], v177, s[50:51]
	ds_read_b128 v[188:191], v169
	ds_read_b128 v[192:195], v170
	s_waitcnt lgkmcnt(4)
	v_mfma_f32_16x16x32_fp8_fp8 v[196:199], v[180:181], v[134:135], 0
	v_mfma_f32_16x16x32_fp8_fp8 v[196:199], v[182:183], v[136:137], v[196:199]
	v_mfma_f32_16x16x32_fp8_fp8 v[196:199], v[184:185], v[138:139], v[196:199]
	v_mfma_f32_16x16x32_fp8_fp8 v[196:199], v[186:187], v[140:141], v[196:199]
	s_waitcnt vmcnt(16)
	ds_write_b128 v168, v[18:21]
	ds_write_b128 v168, v[22:25] offset:1024
	v_lshl_add_u32 v174, v154, 10, v166
	global_load_dwordx4 v[18:21], v174, s[50:51]
	v_lshl_add_u32 v175, v155, 10, v167
	global_load_dwordx4 v[22:25], v175, s[50:51]
	ds_read_b128 v[180:183], v169
	ds_read_b128 v[184:187], v170
	s_waitcnt lgkmcnt(4)
	v_mfma_f32_16x16x32_fp8_fp8 v[200:203], v[188:189], v[134:135], 0
	v_mfma_f32_16x16x32_fp8_fp8 v[200:203], v[190:191], v[136:137], v[200:203]
	v_mfma_f32_16x16x32_fp8_fp8 v[200:203], v[192:193], v[138:139], v[200:203]
	v_mfma_f32_16x16x32_fp8_fp8 v[200:203], v[194:195], v[140:141], v[200:203]
	v_cndmask_b32_e64 v226, v196, v198, s[54:55]
	v_cndmask_b32_e64 v227, v197, v199, s[54:55]
	s_waitcnt vmcnt(16)
	ds_write_b128 v168, v[26:29]
	ds_write_b128 v168, v[30:33] offset:1024
	v_lshl_add_u32 v176, v156, 10, v166
	global_load_dwordx4 v[26:29], v176, s[50:51]
	v_lshl_add_u32 v177, v157, 10, v167
	global_load_dwordx4 v[30:33], v177, s[50:51]
	ds_read_b128 v[188:191], v169
	ds_read_b128 v[192:195], v170
	s_waitcnt lgkmcnt(4)
	v_mfma_f32_16x16x32_fp8_fp8 v[204:207], v[180:181], v[134:135], 0
	v_mfma_f32_16x16x32_fp8_fp8 v[204:207], v[182:183], v[136:137], v[204:207]
	v_mfma_f32_16x16x32_fp8_fp8 v[204:207], v[184:185], v[138:139], v[204:207]
	v_mfma_f32_16x16x32_fp8_fp8 v[204:207], v[186:187], v[140:141], v[204:207]
	v_cndmask_b32_e64 v228, v200, v202, s[54:55]
	v_cndmask_b32_e64 v229, v201, v203, s[54:55]
	v_cndmask_b32_e64 v230, v226, v228, s[56:57]
	v_cndmask_b32_e64 v231, v227, v229, s[56:57]
	s_waitcnt vmcnt(16)
	ds_write_b128 v168, v[34:37]
	ds_write_b128 v168, v[38:41] offset:1024
	v_lshl_add_u32 v174, v158, 10, v166
	global_load_dwordx4 v[34:37], v174, s[50:51]
	v_lshl_add_u32 v175, v159, 10, v167
	global_load_dwordx4 v[38:41], v175, s[50:51]
	ds_read_b128 v[180:183], v169
	ds_read_b128 v[184:187], v170
	s_waitcnt lgkmcnt(4)
	v_mfma_f32_16x16x32_fp8_fp8 v[216:219], v[188:189], v[134:135], 0
	v_mfma_f32_16x16x32_fp8_fp8 v[216:219], v[190:191], v[136:137], v[216:219]
	v_mfma_f32_16x16x32_fp8_fp8 v[216:219], v[192:193], v[138:139], v[216:219]
	v_mfma_f32_16x16x32_fp8_fp8 v[216:219], v[194:195], v[140:141], v[216:219]
	v_cndmask_b32_e64 v226, v204, v206, s[54:55]
	v_cndmask_b32_e64 v227, v205, v207, s[54:55]
	s_waitcnt vmcnt(16)
	ds_write_b128 v168, v[42:45]
	ds_write_b128 v168, v[46:49] offset:1024
	v_lshl_add_u32 v176, v160, 10, v166
	global_load_dwordx4 v[42:45], v176, s[50:51]
	v_lshl_add_u32 v177, v161, 10, v167
	global_load_dwordx4 v[46:49], v177, s[50:51]
	ds_read_b128 v[188:191], v169
	ds_read_b128 v[192:195], v170
	s_waitcnt lgkmcnt(4)
	v_mfma_f32_16x16x32_fp8_fp8 v[196:199], v[180:181], v[134:135], 0
	v_mfma_f32_16x16x32_fp8_fp8 v[196:199], v[182:183], v[136:137], v[196:199]
	v_mfma_f32_16x16x32_fp8_fp8 v[196:199], v[184:185], v[138:139], v[196:199]
	v_mfma_f32_16x16x32_fp8_fp8 v[196:199], v[186:187], v[140:141], v[196:199]
	v_cndmask_b32_e64 v228, v216, v218, s[54:55]
	v_cndmask_b32_e64 v229, v217, v219, s[54:55]
	v_cndmask_b32_e64 v232, v226, v228, s[56:57]
	v_cndmask_b32_e64 v233, v227, v229, s[56:57]
	s_waitcnt vmcnt(16)
	ds_write_b128 v168, v[50:53]
	ds_write_b128 v168, v[54:57] offset:1024
	v_lshl_add_u32 v174, v162, 10, v166
	global_load_dwordx4 v[50:53], v174, s[50:51]
	v_lshl_add_u32 v175, v163, 10, v167
	global_load_dwordx4 v[54:57], v175, s[50:51]
	ds_read_b128 v[180:183], v169
	ds_read_b128 v[184:187], v170
	s_waitcnt lgkmcnt(4)
	v_mfma_f32_16x16x32_fp8_fp8 v[200:203], v[188:189], v[134:135], 0
	v_mfma_f32_16x16x32_fp8_fp8 v[200:203], v[190:191], v[136:137], v[200:203]
	v_mfma_f32_16x16x32_fp8_fp8 v[200:203], v[192:193], v[138:139], v[200:203]
	v_mfma_f32_16x16x32_fp8_fp8 v[200:203], v[194:195], v[140:141], v[200:203]
	v_cndmask_b32_e64 v226, v196, v198, s[54:55]
	v_cndmask_b32_e64 v227, v197, v199, s[54:55]
	s_waitcnt vmcnt(16)
	ds_write_b128 v168, v[58:61]
	ds_write_b128 v168, v[62:65] offset:1024
	v_lshl_add_u32 v176, v164, 10, v166
	global_load_dwordx4 v[58:61], v176, s[50:51]
	v_lshl_add_u32 v177, v165, 10, v167
	global_load_dwordx4 v[62:65], v177, s[50:51]
	ds_read_b128 v[188:191], v169
	ds_read_b128 v[192:195], v170
	s_waitcnt lgkmcnt(4)
	v_mfma_f32_16x16x32_fp8_fp8 v[204:207], v[180:181], v[134:135], 0
	v_mfma_f32_16x16x32_fp8_fp8 v[204:207], v[182:183], v[136:137], v[204:207]
	v_mfma_f32_16x16x32_fp8_fp8 v[204:207], v[184:185], v[138:139], v[204:207]
	v_mfma_f32_16x16x32_fp8_fp8 v[204:207], v[186:187], v[140:141], v[204:207]
	v_cndmask_b32_e64 v228, v200, v202, s[54:55]
	v_cndmask_b32_e64 v229, v201, v203, s[54:55]
	v_cndmask_b32_e64 v234, v226, v228, s[56:57]
	v_cndmask_b32_e64 v235, v227, v229, s[56:57]
	s_waitcnt lgkmcnt(0)
	v_mfma_f32_16x16x32_fp8_fp8 v[216:219], v[188:189], v[134:135], 0
	v_mfma_f32_16x16x32_fp8_fp8 v[216:219], v[190:191], v[136:137], v[216:219]
	v_mfma_f32_16x16x32_fp8_fp8 v[216:219], v[192:193], v[138:139], v[216:219]
	v_mfma_f32_16x16x32_fp8_fp8 v[216:219], v[194:195], v[140:141], v[216:219]
	v_add_u32_e32 v0, 2048, v172
	ds_read2_b32 v[150:151], v0 offset0:0 offset1:8
	ds_read2_b32 v[152:153], v0 offset0:16 offset1:24
	ds_read2_b32 v[154:155], v0 offset0:32 offset1:40
	ds_read2_b32 v[156:157], v0 offset0:48 offset1:56
	ds_read2_b32 v[158:159], v0 offset0:64 offset1:72
	ds_read2_b32 v[160:161], v0 offset0:80 offset1:88
	ds_read2_b32 v[162:163], v0 offset0:96 offset1:104
	ds_read2_b32 v[164:165], v0 offset0:112 offset1:120
	v_add_u32_e32 v171, s80, v171
	global_load_dwordx4 v[134:137], v171, s[52:53]
	global_load_dwordx4 v[138:141], v171, s[52:53] offset:16
	v_cndmask_b32_e64 v226, v204, v206, s[54:55]
	v_cndmask_b32_e64 v227, v205, v207, s[54:55]
	v_cndmask_b32_e64 v228, v216, v218, s[54:55]
	v_cndmask_b32_e64 v229, v217, v219, s[54:55]
	v_cndmask_b32_e64 v236, v226, v228, s[56:57]
	v_cndmask_b32_e64 v237, v227, v229, s[56:57]
	v_cndmask_b32_e64 v226, v230, v232, s[58:59]
	v_cndmask_b32_e64 v228, v234, v236, s[58:59]
	v_cndmask_b32_e64 v227, v231, v233, s[58:59]
	v_cndmask_b32_e64 v229, v235, v237, s[58:59]
	v_cndmask_b32_e64 v226, v226, v228, s[60:61]
	v_cndmask_b32_e64 v227, v227, v229, s[60:61]
	v_add_f32_e32 v246, v246, v226
	v_add_f32_e32 v247, v247, v227
	s_waitcnt vmcnt(16)
	ds_write_b128 v168, v[2:5]
	ds_write_b128 v168, v[6:9] offset:1024
	s_waitcnt lgkmcnt(2)
	v_lshl_add_u32 v174, v150, 10, v166
	global_load_dwordx4 v[2:5], v174, s[50:51]
	v_lshl_add_u32 v175, v151, 10, v167
	global_load_dwordx4 v[6:9], v175, s[50:51]
	ds_read_b128 v[180:183], v169
	ds_read_b128 v[184:187], v170
	s_waitcnt vmcnt(16)
	ds_write_b128 v168, v[10:13]
	ds_write_b128 v168, v[14:17] offset:1024
	v_lshl_add_u32 v176, v152, 10, v166
	global_load_dwordx4 v[10:13], v176, s[50:51]
	v_lshl_add_u32 v177, v153, 10, v167
	global_load_dwordx4 v[14:17], v177, s[50:51]
	ds_read_b128 v[188:191], v169
	ds_read_b128 v[192:195], v170
	s_waitcnt lgkmcnt(4)
	v_mfma_f32_16x16x32_fp8_fp8 v[196:199], v[180:181], v[142:143], 0
	v_mfma_f32_16x16x32_fp8_fp8 v[196:199], v[182:183], v[144:145], v[196:199]
	v_mfma_f32_16x16x32_fp8_fp8 v[196:199], v[184:185], v[146:147], v[196:199]
	v_mfma_f32_16x16x32_fp8_fp8 v[196:199], v[186:187], v[148:149], v[196:199]
	s_waitcnt vmcnt(16)
	ds_write_b128 v168, v[18:21]
	ds_write_b128 v168, v[22:25] offset:1024
	v_lshl_add_u32 v174, v154, 10, v166
	global_load_dwordx4 v[18:21], v174, s[50:51]
	v_lshl_add_u32 v175, v155, 10, v167
	global_load_dwordx4 v[22:25], v175, s[50:51]
	ds_read_b128 v[180:183], v169
	ds_read_b128 v[184:187], v170
	s_waitcnt lgkmcnt(4)
	v_mfma_f32_16x16x32_fp8_fp8 v[200:203], v[188:189], v[142:143], 0
	v_mfma_f32_16x16x32_fp8_fp8 v[200:203], v[190:191], v[144:145], v[200:203]
	v_mfma_f32_16x16x32_fp8_fp8 v[200:203], v[192:193], v[146:147], v[200:203]
	v_mfma_f32_16x16x32_fp8_fp8 v[200:203], v[194:195], v[148:149], v[200:203]
	v_cndmask_b32_e64 v226, v196, v198, s[54:55]
	v_cndmask_b32_e64 v227, v197, v199, s[54:55]
	s_waitcnt vmcnt(16)
	ds_write_b128 v168, v[26:29]
	ds_write_b128 v168, v[30:33] offset:1024
	v_lshl_add_u32 v176, v156, 10, v166
	global_load_dwordx4 v[26:29], v176, s[50:51]
	v_lshl_add_u32 v177, v157, 10, v167
	global_load_dwordx4 v[30:33], v177, s[50:51]
	ds_read_b128 v[188:191], v169
	ds_read_b128 v[192:195], v170
	s_waitcnt lgkmcnt(4)
	v_mfma_f32_16x16x32_fp8_fp8 v[204:207], v[180:181], v[142:143], 0
	v_mfma_f32_16x16x32_fp8_fp8 v[204:207], v[182:183], v[144:145], v[204:207]
	v_mfma_f32_16x16x32_fp8_fp8 v[204:207], v[184:185], v[146:147], v[204:207]
	v_mfma_f32_16x16x32_fp8_fp8 v[204:207], v[186:187], v[148:149], v[204:207]
	v_cndmask_b32_e64 v228, v200, v202, s[54:55]
	v_cndmask_b32_e64 v229, v201, v203, s[54:55]
	v_cndmask_b32_e64 v230, v226, v228, s[56:57]
	v_cndmask_b32_e64 v231, v227, v229, s[56:57]
	s_waitcnt vmcnt(16)
	ds_write_b128 v168, v[34:37]
	ds_write_b128 v168, v[38:41] offset:1024
	v_lshl_add_u32 v174, v158, 10, v166
	global_load_dwordx4 v[34:37], v174, s[50:51]
	v_lshl_add_u32 v175, v159, 10, v167
	global_load_dwordx4 v[38:41], v175, s[50:51]
	ds_read_b128 v[180:183], v169
	ds_read_b128 v[184:187], v170
	s_waitcnt lgkmcnt(4)
	v_mfma_f32_16x16x32_fp8_fp8 v[216:219], v[188:189], v[142:143], 0
	v_mfma_f32_16x16x32_fp8_fp8 v[216:219], v[190:191], v[144:145], v[216:219]
	v_mfma_f32_16x16x32_fp8_fp8 v[216:219], v[192:193], v[146:147], v[216:219]
	v_mfma_f32_16x16x32_fp8_fp8 v[216:219], v[194:195], v[148:149], v[216:219]
	v_cndmask_b32_e64 v226, v204, v206, s[54:55]
	v_cndmask_b32_e64 v227, v205, v207, s[54:55]
	s_waitcnt vmcnt(16)
	ds_write_b128 v168, v[42:45]
	ds_write_b128 v168, v[46:49] offset:1024
	v_lshl_add_u32 v176, v160, 10, v166
	global_load_dwordx4 v[42:45], v176, s[50:51]
	v_lshl_add_u32 v177, v161, 10, v167
	global_load_dwordx4 v[46:49], v177, s[50:51]
	ds_read_b128 v[188:191], v169
	ds_read_b128 v[192:195], v170
	s_waitcnt lgkmcnt(4)
	v_mfma_f32_16x16x32_fp8_fp8 v[196:199], v[180:181], v[142:143], 0
	v_mfma_f32_16x16x32_fp8_fp8 v[196:199], v[182:183], v[144:145], v[196:199]
	v_mfma_f32_16x16x32_fp8_fp8 v[196:199], v[184:185], v[146:147], v[196:199]
	v_mfma_f32_16x16x32_fp8_fp8 v[196:199], v[186:187], v[148:149], v[196:199]
	v_cndmask_b32_e64 v228, v216, v218, s[54:55]
	v_cndmask_b32_e64 v229, v217, v219, s[54:55]
	v_cndmask_b32_e64 v232, v226, v228, s[56:57]
	v_cndmask_b32_e64 v233, v227, v229, s[56:57]
	s_waitcnt vmcnt(16)
	ds_write_b128 v168, v[50:53]
	ds_write_b128 v168, v[54:57] offset:1024
	v_lshl_add_u32 v174, v162, 10, v166
	global_load_dwordx4 v[50:53], v174, s[50:51]
	v_lshl_add_u32 v175, v163, 10, v167
	global_load_dwordx4 v[54:57], v175, s[50:51]
	ds_read_b128 v[180:183], v169
	ds_read_b128 v[184:187], v170
	s_waitcnt lgkmcnt(4)
	v_mfma_f32_16x16x32_fp8_fp8 v[200:203], v[188:189], v[142:143], 0
	v_mfma_f32_16x16x32_fp8_fp8 v[200:203], v[190:191], v[144:145], v[200:203]
	v_mfma_f32_16x16x32_fp8_fp8 v[200:203], v[192:193], v[146:147], v[200:203]
	v_mfma_f32_16x16x32_fp8_fp8 v[200:203], v[194:195], v[148:149], v[200:203]
	v_cndmask_b32_e64 v226, v196, v198, s[54:55]
	v_cndmask_b32_e64 v227, v197, v199, s[54:55]
	s_waitcnt vmcnt(16)
	ds_write_b128 v168, v[58:61]
	ds_write_b128 v168, v[62:65] offset:1024
	v_lshl_add_u32 v176, v164, 10, v166
	global_load_dwordx4 v[58:61], v176, s[50:51]
	v_lshl_add_u32 v177, v165, 10, v167
	global_load_dwordx4 v[62:65], v177, s[50:51]
	ds_read_b128 v[188:191], v169
	ds_read_b128 v[192:195], v170
	s_waitcnt lgkmcnt(4)
	v_mfma_f32_16x16x32_fp8_fp8 v[204:207], v[180:181], v[142:143], 0
	v_mfma_f32_16x16x32_fp8_fp8 v[204:207], v[182:183], v[144:145], v[204:207]
	v_mfma_f32_16x16x32_fp8_fp8 v[204:207], v[184:185], v[146:147], v[204:207]
	v_mfma_f32_16x16x32_fp8_fp8 v[204:207], v[186:187], v[148:149], v[204:207]
	v_cndmask_b32_e64 v228, v200, v202, s[54:55]
	v_cndmask_b32_e64 v229, v201, v203, s[54:55]
	v_cndmask_b32_e64 v234, v226, v228, s[56:57]
	v_cndmask_b32_e64 v235, v227, v229, s[56:57]
	s_waitcnt lgkmcnt(0)
	v_mfma_f32_16x16x32_fp8_fp8 v[216:219], v[188:189], v[142:143], 0
	v_mfma_f32_16x16x32_fp8_fp8 v[216:219], v[190:191], v[144:145], v[216:219]
	v_mfma_f32_16x16x32_fp8_fp8 v[216:219], v[192:193], v[146:147], v[216:219]
	v_mfma_f32_16x16x32_fp8_fp8 v[216:219], v[194:195], v[148:149], v[216:219]
	v_add_u32_e32 v0, 2560, v172
	ds_read2_b32 v[150:151], v0 offset0:0 offset1:8
	ds_read2_b32 v[152:153], v0 offset0:16 offset1:24
	ds_read2_b32 v[154:155], v0 offset0:32 offset1:40
	ds_read2_b32 v[156:157], v0 offset0:48 offset1:56
	ds_read2_b32 v[158:159], v0 offset0:64 offset1:72
	ds_read2_b32 v[160:161], v0 offset0:80 offset1:88
	ds_read2_b32 v[162:163], v0 offset0:96 offset1:104
	ds_read2_b32 v[164:165], v0 offset0:112 offset1:120
	v_add_u32_e32 v171, s80, v171
	global_load_dwordx4 v[142:145], v171, s[52:53]
	global_load_dwordx4 v[146:149], v171, s[52:53] offset:16
	v_cndmask_b32_e64 v226, v204, v206, s[54:55]
	v_cndmask_b32_e64 v227, v205, v207, s[54:55]
	v_cndmask_b32_e64 v228, v216, v218, s[54:55]
	v_cndmask_b32_e64 v229, v217, v219, s[54:55]
	v_cndmask_b32_e64 v236, v226, v228, s[56:57]
	v_cndmask_b32_e64 v237, v227, v229, s[56:57]
	v_cndmask_b32_e64 v226, v230, v232, s[58:59]
	v_cndmask_b32_e64 v228, v234, v236, s[58:59]
	v_cndmask_b32_e64 v227, v231, v233, s[58:59]
	v_cndmask_b32_e64 v229, v235, v237, s[58:59]
	v_cndmask_b32_e64 v226, v226, v228, s[60:61]
	v_cndmask_b32_e64 v227, v227, v229, s[60:61]
	v_add_f32_e32 v248, v248, v226
	v_add_f32_e32 v249, v249, v227
	s_waitcnt vmcnt(16)
	ds_write_b128 v168, v[2:5]
	ds_write_b128 v168, v[6:9] offset:1024
	s_waitcnt lgkmcnt(2)
	v_lshl_add_u32 v174, v150, 10, v166
	global_load_dwordx4 v[2:5], v174, s[50:51]
	v_lshl_add_u32 v175, v151, 10, v167
	global_load_dwordx4 v[6:9], v175, s[50:51]
	ds_read_b128 v[180:183], v169
	ds_read_b128 v[184:187], v170
	s_waitcnt vmcnt(16)
	ds_write_b128 v168, v[10:13]
	ds_write_b128 v168, v[14:17] offset:1024
	v_lshl_add_u32 v176, v152, 10, v166
	global_load_dwordx4 v[10:13], v176, s[50:51]
	v_lshl_add_u32 v177, v153, 10, v167
	global_load_dwordx4 v[14:17], v177, s[50:51]
	ds_read_b128 v[188:191], v169
	ds_read_b128 v[192:195], v170
	s_waitcnt lgkmcnt(4)
	v_mfma_f32_16x16x32_fp8_fp8 v[196:199], v[180:181], v[134:135], 0
	v_mfma_f32_16x16x32_fp8_fp8 v[196:199], v[182:183], v[136:137], v[196:199]
	v_mfma_f32_16x16x32_fp8_fp8 v[196:199], v[184:185], v[138:139], v[196:199]
	v_mfma_f32_16x16x32_fp8_fp8 v[196:199], v[186:187], v[140:141], v[196:199]
	s_waitcnt vmcnt(16)
	ds_write_b128 v168, v[18:21]
	ds_write_b128 v168, v[22:25] offset:1024
	v_lshl_add_u32 v174, v154, 10, v166
	global_load_dwordx4 v[18:21], v174, s[50:51]
	v_lshl_add_u32 v175, v155, 10, v167
	global_load_dwordx4 v[22:25], v175, s[50:51]
	ds_read_b128 v[180:183], v169
	ds_read_b128 v[184:187], v170
	s_waitcnt lgkmcnt(4)
	v_mfma_f32_16x16x32_fp8_fp8 v[200:203], v[188:189], v[134:135], 0
	v_mfma_f32_16x16x32_fp8_fp8 v[200:203], v[190:191], v[136:137], v[200:203]
	v_mfma_f32_16x16x32_fp8_fp8 v[200:203], v[192:193], v[138:139], v[200:203]
	v_mfma_f32_16x16x32_fp8_fp8 v[200:203], v[194:195], v[140:141], v[200:203]
	v_cndmask_b32_e64 v226, v196, v198, s[54:55]
	v_cndmask_b32_e64 v227, v197, v199, s[54:55]
	s_waitcnt vmcnt(16)
	ds_write_b128 v168, v[26:29]
	ds_write_b128 v168, v[30:33] offset:1024
	v_lshl_add_u32 v176, v156, 10, v166
	global_load_dwordx4 v[26:29], v176, s[50:51]
	v_lshl_add_u32 v177, v157, 10, v167
	global_load_dwordx4 v[30:33], v177, s[50:51]
	ds_read_b128 v[188:191], v169
	ds_read_b128 v[192:195], v170
	s_waitcnt lgkmcnt(4)
	v_mfma_f32_16x16x32_fp8_fp8 v[204:207], v[180:181], v[134:135], 0
	v_mfma_f32_16x16x32_fp8_fp8 v[204:207], v[182:183], v[136:137], v[204:207]
	v_mfma_f32_16x16x32_fp8_fp8 v[204:207], v[184:185], v[138:139], v[204:207]
	v_mfma_f32_16x16x32_fp8_fp8 v[204:207], v[186:187], v[140:141], v[204:207]
	v_cndmask_b32_e64 v228, v200, v202, s[54:55]
	v_cndmask_b32_e64 v229, v201, v203, s[54:55]
	v_cndmask_b32_e64 v230, v226, v228, s[56:57]
	v_cndmask_b32_e64 v231, v227, v229, s[56:57]
	s_waitcnt vmcnt(16)
	ds_write_b128 v168, v[34:37]
	ds_write_b128 v168, v[38:41] offset:1024
	v_lshl_add_u32 v174, v158, 10, v166
	global_load_dwordx4 v[34:37], v174, s[50:51]
	v_lshl_add_u32 v175, v159, 10, v167
	global_load_dwordx4 v[38:41], v175, s[50:51]
	ds_read_b128 v[180:183], v169
	ds_read_b128 v[184:187], v170
	s_waitcnt lgkmcnt(4)
	v_mfma_f32_16x16x32_fp8_fp8 v[216:219], v[188:189], v[134:135], 0
	v_mfma_f32_16x16x32_fp8_fp8 v[216:219], v[190:191], v[136:137], v[216:219]
	v_mfma_f32_16x16x32_fp8_fp8 v[216:219], v[192:193], v[138:139], v[216:219]
	v_mfma_f32_16x16x32_fp8_fp8 v[216:219], v[194:195], v[140:141], v[216:219]
	v_cndmask_b32_e64 v226, v204, v206, s[54:55]
	v_cndmask_b32_e64 v227, v205, v207, s[54:55]
	s_waitcnt vmcnt(16)
	ds_write_b128 v168, v[42:45]
	ds_write_b128 v168, v[46:49] offset:1024
	v_lshl_add_u32 v176, v160, 10, v166
	global_load_dwordx4 v[42:45], v176, s[50:51]
	v_lshl_add_u32 v177, v161, 10, v167
	global_load_dwordx4 v[46:49], v177, s[50:51]
	ds_read_b128 v[188:191], v169
	ds_read_b128 v[192:195], v170
	s_waitcnt lgkmcnt(4)
	v_mfma_f32_16x16x32_fp8_fp8 v[196:199], v[180:181], v[134:135], 0
	v_mfma_f32_16x16x32_fp8_fp8 v[196:199], v[182:183], v[136:137], v[196:199]
	v_mfma_f32_16x16x32_fp8_fp8 v[196:199], v[184:185], v[138:139], v[196:199]
	v_mfma_f32_16x16x32_fp8_fp8 v[196:199], v[186:187], v[140:141], v[196:199]
	v_cndmask_b32_e64 v228, v216, v218, s[54:55]
	v_cndmask_b32_e64 v229, v217, v219, s[54:55]
	v_cndmask_b32_e64 v232, v226, v228, s[56:57]
	v_cndmask_b32_e64 v233, v227, v229, s[56:57]
	s_waitcnt vmcnt(16)
	ds_write_b128 v168, v[50:53]
	ds_write_b128 v168, v[54:57] offset:1024
	v_lshl_add_u32 v174, v162, 10, v166
	global_load_dwordx4 v[50:53], v174, s[50:51]
	v_lshl_add_u32 v175, v163, 10, v167
	global_load_dwordx4 v[54:57], v175, s[50:51]
	ds_read_b128 v[180:183], v169
	ds_read_b128 v[184:187], v170
	s_waitcnt lgkmcnt(4)
	v_mfma_f32_16x16x32_fp8_fp8 v[200:203], v[188:189], v[134:135], 0
	v_mfma_f32_16x16x32_fp8_fp8 v[200:203], v[190:191], v[136:137], v[200:203]
	v_mfma_f32_16x16x32_fp8_fp8 v[200:203], v[192:193], v[138:139], v[200:203]
	v_mfma_f32_16x16x32_fp8_fp8 v[200:203], v[194:195], v[140:141], v[200:203]
	v_cndmask_b32_e64 v226, v196, v198, s[54:55]
	v_cndmask_b32_e64 v227, v197, v199, s[54:55]
	s_waitcnt vmcnt(16)
	ds_write_b128 v168, v[58:61]
	ds_write_b128 v168, v[62:65] offset:1024
	v_lshl_add_u32 v176, v164, 10, v166
	global_load_dwordx4 v[58:61], v176, s[50:51]
	v_lshl_add_u32 v177, v165, 10, v167
	global_load_dwordx4 v[62:65], v177, s[50:51]
	ds_read_b128 v[188:191], v169
	ds_read_b128 v[192:195], v170
	s_waitcnt lgkmcnt(4)
	v_mfma_f32_16x16x32_fp8_fp8 v[204:207], v[180:181], v[134:135], 0
	v_mfma_f32_16x16x32_fp8_fp8 v[204:207], v[182:183], v[136:137], v[204:207]
	v_mfma_f32_16x16x32_fp8_fp8 v[204:207], v[184:185], v[138:139], v[204:207]
	v_mfma_f32_16x16x32_fp8_fp8 v[204:207], v[186:187], v[140:141], v[204:207]
	v_cndmask_b32_e64 v228, v200, v202, s[54:55]
	v_cndmask_b32_e64 v229, v201, v203, s[54:55]
	v_cndmask_b32_e64 v234, v226, v228, s[56:57]
	v_cndmask_b32_e64 v235, v227, v229, s[56:57]
	s_waitcnt lgkmcnt(0)
	v_mfma_f32_16x16x32_fp8_fp8 v[216:219], v[188:189], v[134:135], 0
	v_mfma_f32_16x16x32_fp8_fp8 v[216:219], v[190:191], v[136:137], v[216:219]
	v_mfma_f32_16x16x32_fp8_fp8 v[216:219], v[192:193], v[138:139], v[216:219]
	v_mfma_f32_16x16x32_fp8_fp8 v[216:219], v[194:195], v[140:141], v[216:219]
	v_add_u32_e32 v0, 3072, v172
	ds_read2_b32 v[150:151], v0 offset0:0 offset1:8
	ds_read2_b32 v[152:153], v0 offset0:16 offset1:24
	ds_read2_b32 v[154:155], v0 offset0:32 offset1:40
	ds_read2_b32 v[156:157], v0 offset0:48 offset1:56
	ds_read2_b32 v[158:159], v0 offset0:64 offset1:72
	ds_read2_b32 v[160:161], v0 offset0:80 offset1:88
	ds_read2_b32 v[162:163], v0 offset0:96 offset1:104
	ds_read2_b32 v[164:165], v0 offset0:112 offset1:120
	v_add_u32_e32 v171, s80, v171
	global_load_dwordx4 v[134:137], v171, s[52:53]
	global_load_dwordx4 v[138:141], v171, s[52:53] offset:16
	v_cndmask_b32_e64 v226, v204, v206, s[54:55]
	v_cndmask_b32_e64 v227, v205, v207, s[54:55]
	v_cndmask_b32_e64 v228, v216, v218, s[54:55]
	v_cndmask_b32_e64 v229, v217, v219, s[54:55]
	v_cndmask_b32_e64 v236, v226, v228, s[56:57]
	v_cndmask_b32_e64 v237, v227, v229, s[56:57]
	v_cndmask_b32_e64 v226, v230, v232, s[58:59]
	v_cndmask_b32_e64 v228, v234, v236, s[58:59]
	v_cndmask_b32_e64 v227, v231, v233, s[58:59]
	v_cndmask_b32_e64 v229, v235, v237, s[58:59]
	v_cndmask_b32_e64 v226, v226, v228, s[60:61]
	v_cndmask_b32_e64 v227, v227, v229, s[60:61]
	v_add_f32_e32 v238, v238, v226
	v_add_f32_e32 v239, v239, v227
	s_waitcnt vmcnt(16)
	ds_write_b128 v168, v[2:5]
	ds_write_b128 v168, v[6:9] offset:1024
	s_waitcnt lgkmcnt(2)
	v_lshl_add_u32 v174, v150, 10, v166
	global_load_dwordx4 v[2:5], v174, s[50:51]
	v_lshl_add_u32 v175, v151, 10, v167
	global_load_dwordx4 v[6:9], v175, s[50:51]
	ds_read_b128 v[180:183], v169
	ds_read_b128 v[184:187], v170
	s_waitcnt vmcnt(16)
	ds_write_b128 v168, v[10:13]
	ds_write_b128 v168, v[14:17] offset:1024
	v_lshl_add_u32 v176, v152, 10, v166
	global_load_dwordx4 v[10:13], v176, s[50:51]
	v_lshl_add_u32 v177, v153, 10, v167
	global_load_dwordx4 v[14:17], v177, s[50:51]
	ds_read_b128 v[188:191], v169
	ds_read_b128 v[192:195], v170
	s_waitcnt lgkmcnt(4)
	v_mfma_f32_16x16x32_fp8_fp8 v[196:199], v[180:181], v[142:143], 0
	v_mfma_f32_16x16x32_fp8_fp8 v[196:199], v[182:183], v[144:145], v[196:199]
	v_mfma_f32_16x16x32_fp8_fp8 v[196:199], v[184:185], v[146:147], v[196:199]
	v_mfma_f32_16x16x32_fp8_fp8 v[196:199], v[186:187], v[148:149], v[196:199]
	s_waitcnt vmcnt(16)
	ds_write_b128 v168, v[18:21]
	ds_write_b128 v168, v[22:25] offset:1024
	v_lshl_add_u32 v174, v154, 10, v166
	global_load_dwordx4 v[18:21], v174, s[50:51]
	v_lshl_add_u32 v175, v155, 10, v167
	global_load_dwordx4 v[22:25], v175, s[50:51]
	ds_read_b128 v[180:183], v169
	ds_read_b128 v[184:187], v170
	s_waitcnt lgkmcnt(4)
	v_mfma_f32_16x16x32_fp8_fp8 v[200:203], v[188:189], v[142:143], 0
	v_mfma_f32_16x16x32_fp8_fp8 v[200:203], v[190:191], v[144:145], v[200:203]
	v_mfma_f32_16x16x32_fp8_fp8 v[200:203], v[192:193], v[146:147], v[200:203]
	v_mfma_f32_16x16x32_fp8_fp8 v[200:203], v[194:195], v[148:149], v[200:203]
	v_cndmask_b32_e64 v226, v196, v198, s[54:55]
	v_cndmask_b32_e64 v227, v197, v199, s[54:55]
	s_waitcnt vmcnt(16)
	ds_write_b128 v168, v[26:29]
	ds_write_b128 v168, v[30:33] offset:1024
	v_lshl_add_u32 v176, v156, 10, v166
	global_load_dwordx4 v[26:29], v176, s[50:51]
	v_lshl_add_u32 v177, v157, 10, v167
	global_load_dwordx4 v[30:33], v177, s[50:51]
	ds_read_b128 v[188:191], v169
	ds_read_b128 v[192:195], v170
	s_waitcnt lgkmcnt(4)
	v_mfma_f32_16x16x32_fp8_fp8 v[204:207], v[180:181], v[142:143], 0
	v_mfma_f32_16x16x32_fp8_fp8 v[204:207], v[182:183], v[144:145], v[204:207]
	v_mfma_f32_16x16x32_fp8_fp8 v[204:207], v[184:185], v[146:147], v[204:207]
	v_mfma_f32_16x16x32_fp8_fp8 v[204:207], v[186:187], v[148:149], v[204:207]
	v_cndmask_b32_e64 v228, v200, v202, s[54:55]
	v_cndmask_b32_e64 v229, v201, v203, s[54:55]
	v_cndmask_b32_e64 v230, v226, v228, s[56:57]
	v_cndmask_b32_e64 v231, v227, v229, s[56:57]
	s_waitcnt vmcnt(16)
	ds_write_b128 v168, v[34:37]
	ds_write_b128 v168, v[38:41] offset:1024
	v_lshl_add_u32 v174, v158, 10, v166
	global_load_dwordx4 v[34:37], v174, s[50:51]
	v_lshl_add_u32 v175, v159, 10, v167
	global_load_dwordx4 v[38:41], v175, s[50:51]
	ds_read_b128 v[180:183], v169
	ds_read_b128 v[184:187], v170
	s_waitcnt lgkmcnt(4)
	v_mfma_f32_16x16x32_fp8_fp8 v[216:219], v[188:189], v[142:143], 0
	v_mfma_f32_16x16x32_fp8_fp8 v[216:219], v[190:191], v[144:145], v[216:219]
	v_mfma_f32_16x16x32_fp8_fp8 v[216:219], v[192:193], v[146:147], v[216:219]
	v_mfma_f32_16x16x32_fp8_fp8 v[216:219], v[194:195], v[148:149], v[216:219]
	v_cndmask_b32_e64 v226, v204, v206, s[54:55]
	v_cndmask_b32_e64 v227, v205, v207, s[54:55]
	s_waitcnt vmcnt(16)
	ds_write_b128 v168, v[42:45]
	ds_write_b128 v168, v[46:49] offset:1024
	v_lshl_add_u32 v176, v160, 10, v166
	global_load_dwordx4 v[42:45], v176, s[50:51]
	v_lshl_add_u32 v177, v161, 10, v167
	global_load_dwordx4 v[46:49], v177, s[50:51]
	ds_read_b128 v[188:191], v169
	ds_read_b128 v[192:195], v170
	s_waitcnt lgkmcnt(4)
	v_mfma_f32_16x16x32_fp8_fp8 v[196:199], v[180:181], v[142:143], 0
	v_mfma_f32_16x16x32_fp8_fp8 v[196:199], v[182:183], v[144:145], v[196:199]
	v_mfma_f32_16x16x32_fp8_fp8 v[196:199], v[184:185], v[146:147], v[196:199]
	v_mfma_f32_16x16x32_fp8_fp8 v[196:199], v[186:187], v[148:149], v[196:199]
	v_cndmask_b32_e64 v228, v216, v218, s[54:55]
	v_cndmask_b32_e64 v229, v217, v219, s[54:55]
	v_cndmask_b32_e64 v232, v226, v228, s[56:57]
	v_cndmask_b32_e64 v233, v227, v229, s[56:57]
	s_waitcnt vmcnt(16)
	ds_write_b128 v168, v[50:53]
	ds_write_b128 v168, v[54:57] offset:1024
	v_lshl_add_u32 v174, v162, 10, v166
	global_load_dwordx4 v[50:53], v174, s[50:51]
	v_lshl_add_u32 v175, v163, 10, v167
	global_load_dwordx4 v[54:57], v175, s[50:51]
	ds_read_b128 v[180:183], v169
	ds_read_b128 v[184:187], v170
	s_waitcnt lgkmcnt(4)
	v_mfma_f32_16x16x32_fp8_fp8 v[200:203], v[188:189], v[142:143], 0
	v_mfma_f32_16x16x32_fp8_fp8 v[200:203], v[190:191], v[144:145], v[200:203]
	v_mfma_f32_16x16x32_fp8_fp8 v[200:203], v[192:193], v[146:147], v[200:203]
	v_mfma_f32_16x16x32_fp8_fp8 v[200:203], v[194:195], v[148:149], v[200:203]
	v_cndmask_b32_e64 v226, v196, v198, s[54:55]
	v_cndmask_b32_e64 v227, v197, v199, s[54:55]
	s_waitcnt vmcnt(16)
	ds_write_b128 v168, v[58:61]
	ds_write_b128 v168, v[62:65] offset:1024
	v_lshl_add_u32 v176, v164, 10, v166
	global_load_dwordx4 v[58:61], v176, s[50:51]
	v_lshl_add_u32 v177, v165, 10, v167
	global_load_dwordx4 v[62:65], v177, s[50:51]
	ds_read_b128 v[188:191], v169
	ds_read_b128 v[192:195], v170
	s_waitcnt lgkmcnt(4)
	v_mfma_f32_16x16x32_fp8_fp8 v[204:207], v[180:181], v[142:143], 0
	v_mfma_f32_16x16x32_fp8_fp8 v[204:207], v[182:183], v[144:145], v[204:207]
	v_mfma_f32_16x16x32_fp8_fp8 v[204:207], v[184:185], v[146:147], v[204:207]
	v_mfma_f32_16x16x32_fp8_fp8 v[204:207], v[186:187], v[148:149], v[204:207]
	v_cndmask_b32_e64 v228, v200, v202, s[54:55]
	v_cndmask_b32_e64 v229, v201, v203, s[54:55]
	v_cndmask_b32_e64 v234, v226, v228, s[56:57]
	v_cndmask_b32_e64 v235, v227, v229, s[56:57]
	s_waitcnt lgkmcnt(0)
	v_mfma_f32_16x16x32_fp8_fp8 v[216:219], v[188:189], v[142:143], 0
	v_mfma_f32_16x16x32_fp8_fp8 v[216:219], v[190:191], v[144:145], v[216:219]
	v_mfma_f32_16x16x32_fp8_fp8 v[216:219], v[192:193], v[146:147], v[216:219]
	v_mfma_f32_16x16x32_fp8_fp8 v[216:219], v[194:195], v[148:149], v[216:219]
	v_add_u32_e32 v0, 3584, v172
	ds_read2_b32 v[150:151], v0 offset0:0 offset1:8
	ds_read2_b32 v[152:153], v0 offset0:16 offset1:24
	ds_read2_b32 v[154:155], v0 offset0:32 offset1:40
	ds_read2_b32 v[156:157], v0 offset0:48 offset1:56
	ds_read2_b32 v[158:159], v0 offset0:64 offset1:72
	ds_read2_b32 v[160:161], v0 offset0:80 offset1:88
	ds_read2_b32 v[162:163], v0 offset0:96 offset1:104
	ds_read2_b32 v[164:165], v0 offset0:112 offset1:120
	v_add_u32_e32 v171, s80, v171
	global_load_dwordx4 v[142:145], v171, s[52:53]
	global_load_dwordx4 v[146:149], v171, s[52:53] offset:16
	v_cndmask_b32_e64 v226, v204, v206, s[54:55]
	v_cndmask_b32_e64 v227, v205, v207, s[54:55]
	v_cndmask_b32_e64 v228, v216, v218, s[54:55]
	v_cndmask_b32_e64 v229, v217, v219, s[54:55]
	v_cndmask_b32_e64 v236, v226, v228, s[56:57]
	v_cndmask_b32_e64 v237, v227, v229, s[56:57]
	v_cndmask_b32_e64 v226, v230, v232, s[58:59]
	v_cndmask_b32_e64 v228, v234, v236, s[58:59]
	v_cndmask_b32_e64 v227, v231, v233, s[58:59]
	v_cndmask_b32_e64 v229, v235, v237, s[58:59]
	v_cndmask_b32_e64 v226, v226, v228, s[60:61]
	v_cndmask_b32_e64 v227, v227, v229, s[60:61]
	v_add_f32_e32 v240, v240, v226
	v_add_f32_e32 v241, v241, v227
	s_waitcnt vmcnt(16)
	ds_write_b128 v168, v[2:5]
	ds_write_b128 v168, v[6:9] offset:1024
	s_waitcnt lgkmcnt(2)
	v_lshl_add_u32 v174, v150, 10, v166
	global_load_dwordx4 v[2:5], v174, s[50:51]
	v_lshl_add_u32 v175, v151, 10, v167
	global_load_dwordx4 v[6:9], v175, s[50:51]
	ds_read_b128 v[180:183], v169
	ds_read_b128 v[184:187], v170
	s_waitcnt vmcnt(16)
	ds_write_b128 v168, v[10:13]
	ds_write_b128 v168, v[14:17] offset:1024
	v_lshl_add_u32 v176, v152, 10, v166
	global_load_dwordx4 v[10:13], v176, s[50:51]
	v_lshl_add_u32 v177, v153, 10, v167
	global_load_dwordx4 v[14:17], v177, s[50:51]
	ds_read_b128 v[188:191], v169
	ds_read_b128 v[192:195], v170
	s_waitcnt lgkmcnt(4)
	v_mfma_f32_16x16x32_fp8_fp8 v[196:199], v[180:181], v[134:135], 0
	v_mfma_f32_16x16x32_fp8_fp8 v[196:199], v[182:183], v[136:137], v[196:199]
	v_mfma_f32_16x16x32_fp8_fp8 v[196:199], v[184:185], v[138:139], v[196:199]
	v_mfma_f32_16x16x32_fp8_fp8 v[196:199], v[186:187], v[140:141], v[196:199]
	s_waitcnt vmcnt(16)
	ds_write_b128 v168, v[18:21]
	ds_write_b128 v168, v[22:25] offset:1024
	v_lshl_add_u32 v174, v154, 10, v166
	global_load_dwordx4 v[18:21], v174, s[50:51]
	v_lshl_add_u32 v175, v155, 10, v167
	global_load_dwordx4 v[22:25], v175, s[50:51]
	ds_read_b128 v[180:183], v169
	ds_read_b128 v[184:187], v170
	s_waitcnt lgkmcnt(4)
	v_mfma_f32_16x16x32_fp8_fp8 v[200:203], v[188:189], v[134:135], 0
	v_mfma_f32_16x16x32_fp8_fp8 v[200:203], v[190:191], v[136:137], v[200:203]
	v_mfma_f32_16x16x32_fp8_fp8 v[200:203], v[192:193], v[138:139], v[200:203]
	v_mfma_f32_16x16x32_fp8_fp8 v[200:203], v[194:195], v[140:141], v[200:203]
	v_cndmask_b32_e64 v226, v196, v198, s[54:55]
	v_cndmask_b32_e64 v227, v197, v199, s[54:55]
	s_waitcnt vmcnt(16)
	ds_write_b128 v168, v[26:29]
	ds_write_b128 v168, v[30:33] offset:1024
	v_lshl_add_u32 v176, v156, 10, v166
	global_load_dwordx4 v[26:29], v176, s[50:51]
	v_lshl_add_u32 v177, v157, 10, v167
	global_load_dwordx4 v[30:33], v177, s[50:51]
	ds_read_b128 v[188:191], v169
	ds_read_b128 v[192:195], v170
	s_waitcnt lgkmcnt(4)
	v_mfma_f32_16x16x32_fp8_fp8 v[204:207], v[180:181], v[134:135], 0
	v_mfma_f32_16x16x32_fp8_fp8 v[204:207], v[182:183], v[136:137], v[204:207]
	v_mfma_f32_16x16x32_fp8_fp8 v[204:207], v[184:185], v[138:139], v[204:207]
	v_mfma_f32_16x16x32_fp8_fp8 v[204:207], v[186:187], v[140:141], v[204:207]
	v_cndmask_b32_e64 v228, v200, v202, s[54:55]
	v_cndmask_b32_e64 v229, v201, v203, s[54:55]
	v_cndmask_b32_e64 v230, v226, v228, s[56:57]
	v_cndmask_b32_e64 v231, v227, v229, s[56:57]
	s_waitcnt vmcnt(16)
	ds_write_b128 v168, v[34:37]
	ds_write_b128 v168, v[38:41] offset:1024
	v_lshl_add_u32 v174, v158, 10, v166
	global_load_dwordx4 v[34:37], v174, s[50:51]
	v_lshl_add_u32 v175, v159, 10, v167
	global_load_dwordx4 v[38:41], v175, s[50:51]
	ds_read_b128 v[180:183], v169
	ds_read_b128 v[184:187], v170
	s_waitcnt lgkmcnt(4)
	v_mfma_f32_16x16x32_fp8_fp8 v[216:219], v[188:189], v[134:135], 0
	v_mfma_f32_16x16x32_fp8_fp8 v[216:219], v[190:191], v[136:137], v[216:219]
	v_mfma_f32_16x16x32_fp8_fp8 v[216:219], v[192:193], v[138:139], v[216:219]
	v_mfma_f32_16x16x32_fp8_fp8 v[216:219], v[194:195], v[140:141], v[216:219]
	v_cndmask_b32_e64 v226, v204, v206, s[54:55]
	v_cndmask_b32_e64 v227, v205, v207, s[54:55]
	s_waitcnt vmcnt(16)
	ds_write_b128 v168, v[42:45]
	ds_write_b128 v168, v[46:49] offset:1024
	v_lshl_add_u32 v176, v160, 10, v166
	global_load_dwordx4 v[42:45], v176, s[50:51]
	v_lshl_add_u32 v177, v161, 10, v167
	global_load_dwordx4 v[46:49], v177, s[50:51]
	ds_read_b128 v[188:191], v169
	ds_read_b128 v[192:195], v170
	s_waitcnt lgkmcnt(4)
	v_mfma_f32_16x16x32_fp8_fp8 v[196:199], v[180:181], v[134:135], 0
	v_mfma_f32_16x16x32_fp8_fp8 v[196:199], v[182:183], v[136:137], v[196:199]
	v_mfma_f32_16x16x32_fp8_fp8 v[196:199], v[184:185], v[138:139], v[196:199]
	v_mfma_f32_16x16x32_fp8_fp8 v[196:199], v[186:187], v[140:141], v[196:199]
	v_cndmask_b32_e64 v228, v216, v218, s[54:55]
	v_cndmask_b32_e64 v229, v217, v219, s[54:55]
	v_cndmask_b32_e64 v232, v226, v228, s[56:57]
	v_cndmask_b32_e64 v233, v227, v229, s[56:57]
	s_waitcnt vmcnt(16)
	ds_write_b128 v168, v[50:53]
	ds_write_b128 v168, v[54:57] offset:1024
	v_lshl_add_u32 v174, v162, 10, v166
	global_load_dwordx4 v[50:53], v174, s[50:51]
	v_lshl_add_u32 v175, v163, 10, v167
	global_load_dwordx4 v[54:57], v175, s[50:51]
	ds_read_b128 v[180:183], v169
	ds_read_b128 v[184:187], v170
	s_waitcnt lgkmcnt(4)
	v_mfma_f32_16x16x32_fp8_fp8 v[200:203], v[188:189], v[134:135], 0
	v_mfma_f32_16x16x32_fp8_fp8 v[200:203], v[190:191], v[136:137], v[200:203]
	v_mfma_f32_16x16x32_fp8_fp8 v[200:203], v[192:193], v[138:139], v[200:203]
	v_mfma_f32_16x16x32_fp8_fp8 v[200:203], v[194:195], v[140:141], v[200:203]
	v_cndmask_b32_e64 v226, v196, v198, s[54:55]
	v_cndmask_b32_e64 v227, v197, v199, s[54:55]
	s_waitcnt vmcnt(16)
	ds_write_b128 v168, v[58:61]
	ds_write_b128 v168, v[62:65] offset:1024
	v_lshl_add_u32 v176, v164, 10, v166
	global_load_dwordx4 v[58:61], v176, s[50:51]
	v_lshl_add_u32 v177, v165, 10, v167
	global_load_dwordx4 v[62:65], v177, s[50:51]
	ds_read_b128 v[188:191], v169
	ds_read_b128 v[192:195], v170
	s_waitcnt lgkmcnt(4)
	v_mfma_f32_16x16x32_fp8_fp8 v[204:207], v[180:181], v[134:135], 0
	v_mfma_f32_16x16x32_fp8_fp8 v[204:207], v[182:183], v[136:137], v[204:207]
	v_mfma_f32_16x16x32_fp8_fp8 v[204:207], v[184:185], v[138:139], v[204:207]
	v_mfma_f32_16x16x32_fp8_fp8 v[204:207], v[186:187], v[140:141], v[204:207]
	v_cndmask_b32_e64 v228, v200, v202, s[54:55]
	v_cndmask_b32_e64 v229, v201, v203, s[54:55]
	v_cndmask_b32_e64 v234, v226, v228, s[56:57]
	v_cndmask_b32_e64 v235, v227, v229, s[56:57]
	s_waitcnt lgkmcnt(0)
	v_mfma_f32_16x16x32_fp8_fp8 v[216:219], v[188:189], v[134:135], 0
	v_mfma_f32_16x16x32_fp8_fp8 v[216:219], v[190:191], v[136:137], v[216:219]
	v_mfma_f32_16x16x32_fp8_fp8 v[216:219], v[192:193], v[138:139], v[216:219]
	v_mfma_f32_16x16x32_fp8_fp8 v[216:219], v[194:195], v[140:141], v[216:219]
	v_add_u32_e32 v0, 4096, v172
	ds_read2_b32 v[150:151], v0 offset0:0 offset1:8
	ds_read2_b32 v[152:153], v0 offset0:16 offset1:24
	ds_read2_b32 v[154:155], v0 offset0:32 offset1:40
	ds_read2_b32 v[156:157], v0 offset0:48 offset1:56
	ds_read2_b32 v[158:159], v0 offset0:64 offset1:72
	ds_read2_b32 v[160:161], v0 offset0:80 offset1:88
	ds_read2_b32 v[162:163], v0 offset0:96 offset1:104
	ds_read2_b32 v[164:165], v0 offset0:112 offset1:120
	v_add_u32_e32 v171, s80, v171
	global_load_dwordx4 v[134:137], v171, s[52:53]
	global_load_dwordx4 v[138:141], v171, s[52:53] offset:16
	v_cndmask_b32_e64 v226, v204, v206, s[54:55]
	v_cndmask_b32_e64 v227, v205, v207, s[54:55]
	v_cndmask_b32_e64 v228, v216, v218, s[54:55]
	v_cndmask_b32_e64 v229, v217, v219, s[54:55]
	v_cndmask_b32_e64 v236, v226, v228, s[56:57]
	v_cndmask_b32_e64 v237, v227, v229, s[56:57]
	v_cndmask_b32_e64 v226, v230, v232, s[58:59]
	v_cndmask_b32_e64 v228, v234, v236, s[58:59]
	v_cndmask_b32_e64 v227, v231, v233, s[58:59]
	v_cndmask_b32_e64 v229, v235, v237, s[58:59]
	v_cndmask_b32_e64 v226, v226, v228, s[60:61]
	v_cndmask_b32_e64 v227, v227, v229, s[60:61]
	v_add_f32_e32 v94, v94, v226
	v_add_f32_e32 v95, v95, v227
	s_waitcnt vmcnt(16)
	ds_write_b128 v168, v[2:5]
	ds_write_b128 v168, v[6:9] offset:1024
	s_waitcnt lgkmcnt(2)
	v_lshl_add_u32 v174, v150, 10, v166
	global_load_dwordx4 v[2:5], v174, s[50:51]
	v_lshl_add_u32 v175, v151, 10, v167
	global_load_dwordx4 v[6:9], v175, s[50:51]
	ds_read_b128 v[180:183], v169
	ds_read_b128 v[184:187], v170
	s_waitcnt vmcnt(16)
	ds_write_b128 v168, v[10:13]
	ds_write_b128 v168, v[14:17] offset:1024
	v_lshl_add_u32 v176, v152, 10, v166
	global_load_dwordx4 v[10:13], v176, s[50:51]
	v_lshl_add_u32 v177, v153, 10, v167
	global_load_dwordx4 v[14:17], v177, s[50:51]
	ds_read_b128 v[188:191], v169
	ds_read_b128 v[192:195], v170
	s_waitcnt lgkmcnt(4)
	v_mfma_f32_16x16x32_fp8_fp8 v[196:199], v[180:181], v[142:143], 0
	v_mfma_f32_16x16x32_fp8_fp8 v[196:199], v[182:183], v[144:145], v[196:199]
	v_mfma_f32_16x16x32_fp8_fp8 v[196:199], v[184:185], v[146:147], v[196:199]
	v_mfma_f32_16x16x32_fp8_fp8 v[196:199], v[186:187], v[148:149], v[196:199]
	s_waitcnt vmcnt(16)
	ds_write_b128 v168, v[18:21]
	ds_write_b128 v168, v[22:25] offset:1024
	v_lshl_add_u32 v174, v154, 10, v166
	global_load_dwordx4 v[18:21], v174, s[50:51]
	v_lshl_add_u32 v175, v155, 10, v167
	global_load_dwordx4 v[22:25], v175, s[50:51]
	ds_read_b128 v[180:183], v169
	ds_read_b128 v[184:187], v170
	s_waitcnt lgkmcnt(4)
	v_mfma_f32_16x16x32_fp8_fp8 v[200:203], v[188:189], v[142:143], 0
	v_mfma_f32_16x16x32_fp8_fp8 v[200:203], v[190:191], v[144:145], v[200:203]
	v_mfma_f32_16x16x32_fp8_fp8 v[200:203], v[192:193], v[146:147], v[200:203]
	v_mfma_f32_16x16x32_fp8_fp8 v[200:203], v[194:195], v[148:149], v[200:203]
	v_cndmask_b32_e64 v226, v196, v198, s[54:55]
	v_cndmask_b32_e64 v227, v197, v199, s[54:55]
	s_waitcnt vmcnt(16)
	ds_write_b128 v168, v[26:29]
	ds_write_b128 v168, v[30:33] offset:1024
	v_lshl_add_u32 v176, v156, 10, v166
	global_load_dwordx4 v[26:29], v176, s[50:51]
	v_lshl_add_u32 v177, v157, 10, v167
	global_load_dwordx4 v[30:33], v177, s[50:51]
	ds_read_b128 v[188:191], v169
	ds_read_b128 v[192:195], v170
	s_waitcnt lgkmcnt(4)
	v_mfma_f32_16x16x32_fp8_fp8 v[204:207], v[180:181], v[142:143], 0
	v_mfma_f32_16x16x32_fp8_fp8 v[204:207], v[182:183], v[144:145], v[204:207]
	v_mfma_f32_16x16x32_fp8_fp8 v[204:207], v[184:185], v[146:147], v[204:207]
	v_mfma_f32_16x16x32_fp8_fp8 v[204:207], v[186:187], v[148:149], v[204:207]
	v_cndmask_b32_e64 v228, v200, v202, s[54:55]
	v_cndmask_b32_e64 v229, v201, v203, s[54:55]
	v_cndmask_b32_e64 v230, v226, v228, s[56:57]
	v_cndmask_b32_e64 v231, v227, v229, s[56:57]
	s_waitcnt vmcnt(16)
	ds_write_b128 v168, v[34:37]
	ds_write_b128 v168, v[38:41] offset:1024
	v_lshl_add_u32 v174, v158, 10, v166
	global_load_dwordx4 v[34:37], v174, s[50:51]
	v_lshl_add_u32 v175, v159, 10, v167
	global_load_dwordx4 v[38:41], v175, s[50:51]
	ds_read_b128 v[180:183], v169
	ds_read_b128 v[184:187], v170
	s_waitcnt lgkmcnt(4)
	v_mfma_f32_16x16x32_fp8_fp8 v[216:219], v[188:189], v[142:143], 0
	v_mfma_f32_16x16x32_fp8_fp8 v[216:219], v[190:191], v[144:145], v[216:219]
	v_mfma_f32_16x16x32_fp8_fp8 v[216:219], v[192:193], v[146:147], v[216:219]
	v_mfma_f32_16x16x32_fp8_fp8 v[216:219], v[194:195], v[148:149], v[216:219]
	v_cndmask_b32_e64 v226, v204, v206, s[54:55]
	v_cndmask_b32_e64 v227, v205, v207, s[54:55]
	s_waitcnt vmcnt(16)
	ds_write_b128 v168, v[42:45]
	ds_write_b128 v168, v[46:49] offset:1024
	v_lshl_add_u32 v176, v160, 10, v166
	global_load_dwordx4 v[42:45], v176, s[50:51]
	v_lshl_add_u32 v177, v161, 10, v167
	global_load_dwordx4 v[46:49], v177, s[50:51]
	ds_read_b128 v[188:191], v169
	ds_read_b128 v[192:195], v170
	s_waitcnt lgkmcnt(4)
	v_mfma_f32_16x16x32_fp8_fp8 v[196:199], v[180:181], v[142:143], 0
	v_mfma_f32_16x16x32_fp8_fp8 v[196:199], v[182:183], v[144:145], v[196:199]
	v_mfma_f32_16x16x32_fp8_fp8 v[196:199], v[184:185], v[146:147], v[196:199]
	v_mfma_f32_16x16x32_fp8_fp8 v[196:199], v[186:187], v[148:149], v[196:199]
	v_cndmask_b32_e64 v228, v216, v218, s[54:55]
	v_cndmask_b32_e64 v229, v217, v219, s[54:55]
	v_cndmask_b32_e64 v232, v226, v228, s[56:57]
	v_cndmask_b32_e64 v233, v227, v229, s[56:57]
	s_waitcnt vmcnt(16)
	ds_write_b128 v168, v[50:53]
	ds_write_b128 v168, v[54:57] offset:1024
	v_lshl_add_u32 v174, v162, 10, v166
	global_load_dwordx4 v[50:53], v174, s[50:51]
	v_lshl_add_u32 v175, v163, 10, v167
	global_load_dwordx4 v[54:57], v175, s[50:51]
	ds_read_b128 v[180:183], v169
	ds_read_b128 v[184:187], v170
	s_waitcnt lgkmcnt(4)
	v_mfma_f32_16x16x32_fp8_fp8 v[200:203], v[188:189], v[142:143], 0
	v_mfma_f32_16x16x32_fp8_fp8 v[200:203], v[190:191], v[144:145], v[200:203]
	v_mfma_f32_16x16x32_fp8_fp8 v[200:203], v[192:193], v[146:147], v[200:203]
	v_mfma_f32_16x16x32_fp8_fp8 v[200:203], v[194:195], v[148:149], v[200:203]
	v_cndmask_b32_e64 v226, v196, v198, s[54:55]
	v_cndmask_b32_e64 v227, v197, v199, s[54:55]
	s_waitcnt vmcnt(16)
	ds_write_b128 v168, v[58:61]
	ds_write_b128 v168, v[62:65] offset:1024
	v_lshl_add_u32 v176, v164, 10, v166
	global_load_dwordx4 v[58:61], v176, s[50:51]
	v_lshl_add_u32 v177, v165, 10, v167
	global_load_dwordx4 v[62:65], v177, s[50:51]
	ds_read_b128 v[188:191], v169
	ds_read_b128 v[192:195], v170
	s_waitcnt lgkmcnt(4)
	v_mfma_f32_16x16x32_fp8_fp8 v[204:207], v[180:181], v[142:143], 0
	v_mfma_f32_16x16x32_fp8_fp8 v[204:207], v[182:183], v[144:145], v[204:207]
	v_mfma_f32_16x16x32_fp8_fp8 v[204:207], v[184:185], v[146:147], v[204:207]
	v_mfma_f32_16x16x32_fp8_fp8 v[204:207], v[186:187], v[148:149], v[204:207]
	v_cndmask_b32_e64 v228, v200, v202, s[54:55]
	v_cndmask_b32_e64 v229, v201, v203, s[54:55]
	v_cndmask_b32_e64 v234, v226, v228, s[56:57]
	v_cndmask_b32_e64 v235, v227, v229, s[56:57]
	s_waitcnt lgkmcnt(0)
	v_mfma_f32_16x16x32_fp8_fp8 v[216:219], v[188:189], v[142:143], 0
	v_mfma_f32_16x16x32_fp8_fp8 v[216:219], v[190:191], v[144:145], v[216:219]
	v_mfma_f32_16x16x32_fp8_fp8 v[216:219], v[192:193], v[146:147], v[216:219]
	v_mfma_f32_16x16x32_fp8_fp8 v[216:219], v[194:195], v[148:149], v[216:219]
	v_add_u32_e32 v0, 4608, v172
	ds_read2_b32 v[150:151], v0 offset0:0 offset1:8
	ds_read2_b32 v[152:153], v0 offset0:16 offset1:24
	ds_read2_b32 v[154:155], v0 offset0:32 offset1:40
	ds_read2_b32 v[156:157], v0 offset0:48 offset1:56
	ds_read2_b32 v[158:159], v0 offset0:64 offset1:72
	ds_read2_b32 v[160:161], v0 offset0:80 offset1:88
	ds_read2_b32 v[162:163], v0 offset0:96 offset1:104
	ds_read2_b32 v[164:165], v0 offset0:112 offset1:120
	v_add_u32_e32 v171, s80, v171
	global_load_dwordx4 v[142:145], v171, s[52:53]
	global_load_dwordx4 v[146:149], v171, s[52:53] offset:16
	v_cndmask_b32_e64 v226, v204, v206, s[54:55]
	v_cndmask_b32_e64 v227, v205, v207, s[54:55]
	v_cndmask_b32_e64 v228, v216, v218, s[54:55]
	v_cndmask_b32_e64 v229, v217, v219, s[54:55]
	v_cndmask_b32_e64 v236, v226, v228, s[56:57]
	v_cndmask_b32_e64 v237, v227, v229, s[56:57]
	v_cndmask_b32_e64 v226, v230, v232, s[58:59]
	v_cndmask_b32_e64 v228, v234, v236, s[58:59]
	v_cndmask_b32_e64 v227, v231, v233, s[58:59]
	v_cndmask_b32_e64 v229, v235, v237, s[58:59]
	v_cndmask_b32_e64 v226, v226, v228, s[60:61]
	v_cndmask_b32_e64 v227, v227, v229, s[60:61]
	v_add_f32_e32 v96, v96, v226
	v_add_f32_e32 v97, v97, v227
	s_waitcnt vmcnt(16)
	ds_write_b128 v168, v[2:5]
	ds_write_b128 v168, v[6:9] offset:1024
	s_waitcnt lgkmcnt(2)
	v_lshl_add_u32 v174, v150, 10, v166
	global_load_dwordx4 v[2:5], v174, s[50:51]
	v_lshl_add_u32 v175, v151, 10, v167
	global_load_dwordx4 v[6:9], v175, s[50:51]
	ds_read_b128 v[180:183], v169
	ds_read_b128 v[184:187], v170
	s_waitcnt vmcnt(16)
	ds_write_b128 v168, v[10:13]
	ds_write_b128 v168, v[14:17] offset:1024
	v_lshl_add_u32 v176, v152, 10, v166
	global_load_dwordx4 v[10:13], v176, s[50:51]
	v_lshl_add_u32 v177, v153, 10, v167
	global_load_dwordx4 v[14:17], v177, s[50:51]
	ds_read_b128 v[188:191], v169
	ds_read_b128 v[192:195], v170
	s_waitcnt lgkmcnt(4)
	v_mfma_f32_16x16x32_fp8_fp8 v[196:199], v[180:181], v[134:135], 0
	v_mfma_f32_16x16x32_fp8_fp8 v[196:199], v[182:183], v[136:137], v[196:199]
	v_mfma_f32_16x16x32_fp8_fp8 v[196:199], v[184:185], v[138:139], v[196:199]
	v_mfma_f32_16x16x32_fp8_fp8 v[196:199], v[186:187], v[140:141], v[196:199]
	s_waitcnt vmcnt(16)
	ds_write_b128 v168, v[18:21]
	ds_write_b128 v168, v[22:25] offset:1024
	v_lshl_add_u32 v174, v154, 10, v166
	global_load_dwordx4 v[18:21], v174, s[50:51]
	v_lshl_add_u32 v175, v155, 10, v167
	global_load_dwordx4 v[22:25], v175, s[50:51]
	ds_read_b128 v[180:183], v169
	ds_read_b128 v[184:187], v170
	s_waitcnt lgkmcnt(4)
	v_mfma_f32_16x16x32_fp8_fp8 v[200:203], v[188:189], v[134:135], 0
	v_mfma_f32_16x16x32_fp8_fp8 v[200:203], v[190:191], v[136:137], v[200:203]
	v_mfma_f32_16x16x32_fp8_fp8 v[200:203], v[192:193], v[138:139], v[200:203]
	v_mfma_f32_16x16x32_fp8_fp8 v[200:203], v[194:195], v[140:141], v[200:203]
	v_cndmask_b32_e64 v226, v196, v198, s[54:55]
	v_cndmask_b32_e64 v227, v197, v199, s[54:55]
	s_waitcnt vmcnt(16)
	ds_write_b128 v168, v[26:29]
	ds_write_b128 v168, v[30:33] offset:1024
	v_lshl_add_u32 v176, v156, 10, v166
	global_load_dwordx4 v[26:29], v176, s[50:51]
	v_lshl_add_u32 v177, v157, 10, v167
	global_load_dwordx4 v[30:33], v177, s[50:51]
	ds_read_b128 v[188:191], v169
	ds_read_b128 v[192:195], v170
	s_waitcnt lgkmcnt(4)
	v_mfma_f32_16x16x32_fp8_fp8 v[204:207], v[180:181], v[134:135], 0
	v_mfma_f32_16x16x32_fp8_fp8 v[204:207], v[182:183], v[136:137], v[204:207]
	v_mfma_f32_16x16x32_fp8_fp8 v[204:207], v[184:185], v[138:139], v[204:207]
	v_mfma_f32_16x16x32_fp8_fp8 v[204:207], v[186:187], v[140:141], v[204:207]
	v_cndmask_b32_e64 v228, v200, v202, s[54:55]
	v_cndmask_b32_e64 v229, v201, v203, s[54:55]
	v_cndmask_b32_e64 v230, v226, v228, s[56:57]
	v_cndmask_b32_e64 v231, v227, v229, s[56:57]
	s_waitcnt vmcnt(16)
	ds_write_b128 v168, v[34:37]
	ds_write_b128 v168, v[38:41] offset:1024
	v_lshl_add_u32 v174, v158, 10, v166
	global_load_dwordx4 v[34:37], v174, s[50:51]
	v_lshl_add_u32 v175, v159, 10, v167
	global_load_dwordx4 v[38:41], v175, s[50:51]
	ds_read_b128 v[180:183], v169
	ds_read_b128 v[184:187], v170
	s_waitcnt lgkmcnt(4)
	v_mfma_f32_16x16x32_fp8_fp8 v[216:219], v[188:189], v[134:135], 0
	v_mfma_f32_16x16x32_fp8_fp8 v[216:219], v[190:191], v[136:137], v[216:219]
	v_mfma_f32_16x16x32_fp8_fp8 v[216:219], v[192:193], v[138:139], v[216:219]
	v_mfma_f32_16x16x32_fp8_fp8 v[216:219], v[194:195], v[140:141], v[216:219]
	v_cndmask_b32_e64 v226, v204, v206, s[54:55]
	v_cndmask_b32_e64 v227, v205, v207, s[54:55]
	s_waitcnt vmcnt(16)
	ds_write_b128 v168, v[42:45]
	ds_write_b128 v168, v[46:49] offset:1024
	v_lshl_add_u32 v176, v160, 10, v166
	global_load_dwordx4 v[42:45], v176, s[50:51]
	v_lshl_add_u32 v177, v161, 10, v167
	global_load_dwordx4 v[46:49], v177, s[50:51]
	ds_read_b128 v[188:191], v169
	ds_read_b128 v[192:195], v170
	s_waitcnt lgkmcnt(4)
	v_mfma_f32_16x16x32_fp8_fp8 v[196:199], v[180:181], v[134:135], 0
	v_mfma_f32_16x16x32_fp8_fp8 v[196:199], v[182:183], v[136:137], v[196:199]
	v_mfma_f32_16x16x32_fp8_fp8 v[196:199], v[184:185], v[138:139], v[196:199]
	v_mfma_f32_16x16x32_fp8_fp8 v[196:199], v[186:187], v[140:141], v[196:199]
	v_cndmask_b32_e64 v228, v216, v218, s[54:55]
	v_cndmask_b32_e64 v229, v217, v219, s[54:55]
	v_cndmask_b32_e64 v232, v226, v228, s[56:57]
	v_cndmask_b32_e64 v233, v227, v229, s[56:57]
	s_waitcnt vmcnt(16)
	ds_write_b128 v168, v[50:53]
	ds_write_b128 v168, v[54:57] offset:1024
	v_lshl_add_u32 v174, v162, 10, v166
	global_load_dwordx4 v[50:53], v174, s[50:51]
	v_lshl_add_u32 v175, v163, 10, v167
	global_load_dwordx4 v[54:57], v175, s[50:51]
	ds_read_b128 v[180:183], v169
	ds_read_b128 v[184:187], v170
	s_waitcnt lgkmcnt(4)
	v_mfma_f32_16x16x32_fp8_fp8 v[200:203], v[188:189], v[134:135], 0
	v_mfma_f32_16x16x32_fp8_fp8 v[200:203], v[190:191], v[136:137], v[200:203]
	v_mfma_f32_16x16x32_fp8_fp8 v[200:203], v[192:193], v[138:139], v[200:203]
	v_mfma_f32_16x16x32_fp8_fp8 v[200:203], v[194:195], v[140:141], v[200:203]
	v_cndmask_b32_e64 v226, v196, v198, s[54:55]
	v_cndmask_b32_e64 v227, v197, v199, s[54:55]
	s_waitcnt vmcnt(16)
	ds_write_b128 v168, v[58:61]
	ds_write_b128 v168, v[62:65] offset:1024
	v_lshl_add_u32 v176, v164, 10, v166
	global_load_dwordx4 v[58:61], v176, s[50:51]
	v_lshl_add_u32 v177, v165, 10, v167
	global_load_dwordx4 v[62:65], v177, s[50:51]
	ds_read_b128 v[188:191], v169
	ds_read_b128 v[192:195], v170
	s_waitcnt lgkmcnt(4)
	v_mfma_f32_16x16x32_fp8_fp8 v[204:207], v[180:181], v[134:135], 0
	v_mfma_f32_16x16x32_fp8_fp8 v[204:207], v[182:183], v[136:137], v[204:207]
	v_mfma_f32_16x16x32_fp8_fp8 v[204:207], v[184:185], v[138:139], v[204:207]
	v_mfma_f32_16x16x32_fp8_fp8 v[204:207], v[186:187], v[140:141], v[204:207]
	v_cndmask_b32_e64 v228, v200, v202, s[54:55]
	v_cndmask_b32_e64 v229, v201, v203, s[54:55]
	v_cndmask_b32_e64 v234, v226, v228, s[56:57]
	v_cndmask_b32_e64 v235, v227, v229, s[56:57]
	s_waitcnt lgkmcnt(0)
	v_mfma_f32_16x16x32_fp8_fp8 v[216:219], v[188:189], v[134:135], 0
	v_mfma_f32_16x16x32_fp8_fp8 v[216:219], v[190:191], v[136:137], v[216:219]
	v_mfma_f32_16x16x32_fp8_fp8 v[216:219], v[192:193], v[138:139], v[216:219]
	v_mfma_f32_16x16x32_fp8_fp8 v[216:219], v[194:195], v[140:141], v[216:219]
	v_add_u32_e32 v0, 5120, v172
	ds_read2_b32 v[150:151], v0 offset0:0 offset1:8
	ds_read2_b32 v[152:153], v0 offset0:16 offset1:24
	ds_read2_b32 v[154:155], v0 offset0:32 offset1:40
	ds_read2_b32 v[156:157], v0 offset0:48 offset1:56
	ds_read2_b32 v[158:159], v0 offset0:64 offset1:72
	ds_read2_b32 v[160:161], v0 offset0:80 offset1:88
	ds_read2_b32 v[162:163], v0 offset0:96 offset1:104
	ds_read2_b32 v[164:165], v0 offset0:112 offset1:120
	v_add_u32_e32 v171, s80, v171
	global_load_dwordx4 v[134:137], v171, s[52:53]
	global_load_dwordx4 v[138:141], v171, s[52:53] offset:16
	v_cndmask_b32_e64 v226, v204, v206, s[54:55]
	v_cndmask_b32_e64 v227, v205, v207, s[54:55]
	v_cndmask_b32_e64 v228, v216, v218, s[54:55]
	v_cndmask_b32_e64 v229, v217, v219, s[54:55]
	v_cndmask_b32_e64 v236, v226, v228, s[56:57]
	v_cndmask_b32_e64 v237, v227, v229, s[56:57]
	v_cndmask_b32_e64 v226, v230, v232, s[58:59]
	v_cndmask_b32_e64 v228, v234, v236, s[58:59]
	v_cndmask_b32_e64 v227, v231, v233, s[58:59]
	v_cndmask_b32_e64 v229, v235, v237, s[58:59]
	v_cndmask_b32_e64 v226, v226, v228, s[60:61]
	v_cndmask_b32_e64 v227, v227, v229, s[60:61]
	v_add_f32_e32 v98, v98, v226
	v_add_f32_e32 v99, v99, v227
	s_waitcnt vmcnt(16)
	ds_write_b128 v168, v[2:5]
	ds_write_b128 v168, v[6:9] offset:1024
	s_waitcnt lgkmcnt(2)
	v_lshl_add_u32 v174, v150, 10, v166
	global_load_dwordx4 v[2:5], v174, s[50:51]
	v_lshl_add_u32 v175, v151, 10, v167
	global_load_dwordx4 v[6:9], v175, s[50:51]
	ds_read_b128 v[180:183], v169
	ds_read_b128 v[184:187], v170
	s_waitcnt vmcnt(16)
	ds_write_b128 v168, v[10:13]
	ds_write_b128 v168, v[14:17] offset:1024
	v_lshl_add_u32 v176, v152, 10, v166
	global_load_dwordx4 v[10:13], v176, s[50:51]
	v_lshl_add_u32 v177, v153, 10, v167
	global_load_dwordx4 v[14:17], v177, s[50:51]
	ds_read_b128 v[188:191], v169
	ds_read_b128 v[192:195], v170
	s_waitcnt lgkmcnt(4)
	v_mfma_f32_16x16x32_fp8_fp8 v[196:199], v[180:181], v[142:143], 0
	v_mfma_f32_16x16x32_fp8_fp8 v[196:199], v[182:183], v[144:145], v[196:199]
	v_mfma_f32_16x16x32_fp8_fp8 v[196:199], v[184:185], v[146:147], v[196:199]
	v_mfma_f32_16x16x32_fp8_fp8 v[196:199], v[186:187], v[148:149], v[196:199]
	s_waitcnt vmcnt(16)
	ds_write_b128 v168, v[18:21]
	ds_write_b128 v168, v[22:25] offset:1024
	v_lshl_add_u32 v174, v154, 10, v166
	global_load_dwordx4 v[18:21], v174, s[50:51]
	v_lshl_add_u32 v175, v155, 10, v167
	global_load_dwordx4 v[22:25], v175, s[50:51]
	ds_read_b128 v[180:183], v169
	ds_read_b128 v[184:187], v170
	s_waitcnt lgkmcnt(4)
	v_mfma_f32_16x16x32_fp8_fp8 v[200:203], v[188:189], v[142:143], 0
	v_mfma_f32_16x16x32_fp8_fp8 v[200:203], v[190:191], v[144:145], v[200:203]
	v_mfma_f32_16x16x32_fp8_fp8 v[200:203], v[192:193], v[146:147], v[200:203]
	v_mfma_f32_16x16x32_fp8_fp8 v[200:203], v[194:195], v[148:149], v[200:203]
	v_cndmask_b32_e64 v226, v196, v198, s[54:55]
	v_cndmask_b32_e64 v227, v197, v199, s[54:55]
	s_waitcnt vmcnt(16)
	ds_write_b128 v168, v[26:29]
	ds_write_b128 v168, v[30:33] offset:1024
	v_lshl_add_u32 v176, v156, 10, v166
	global_load_dwordx4 v[26:29], v176, s[50:51]
	v_lshl_add_u32 v177, v157, 10, v167
	global_load_dwordx4 v[30:33], v177, s[50:51]
	ds_read_b128 v[188:191], v169
	ds_read_b128 v[192:195], v170
	s_waitcnt lgkmcnt(4)
	v_mfma_f32_16x16x32_fp8_fp8 v[204:207], v[180:181], v[142:143], 0
	v_mfma_f32_16x16x32_fp8_fp8 v[204:207], v[182:183], v[144:145], v[204:207]
	v_mfma_f32_16x16x32_fp8_fp8 v[204:207], v[184:185], v[146:147], v[204:207]
	v_mfma_f32_16x16x32_fp8_fp8 v[204:207], v[186:187], v[148:149], v[204:207]
	v_cndmask_b32_e64 v228, v200, v202, s[54:55]
	v_cndmask_b32_e64 v229, v201, v203, s[54:55]
	v_cndmask_b32_e64 v230, v226, v228, s[56:57]
	v_cndmask_b32_e64 v231, v227, v229, s[56:57]
	s_waitcnt vmcnt(16)
	ds_write_b128 v168, v[34:37]
	ds_write_b128 v168, v[38:41] offset:1024
	v_lshl_add_u32 v174, v158, 10, v166
	global_load_dwordx4 v[34:37], v174, s[50:51]
	v_lshl_add_u32 v175, v159, 10, v167
	global_load_dwordx4 v[38:41], v175, s[50:51]
	ds_read_b128 v[180:183], v169
	ds_read_b128 v[184:187], v170
	s_waitcnt lgkmcnt(4)
	v_mfma_f32_16x16x32_fp8_fp8 v[216:219], v[188:189], v[142:143], 0
	v_mfma_f32_16x16x32_fp8_fp8 v[216:219], v[190:191], v[144:145], v[216:219]
	v_mfma_f32_16x16x32_fp8_fp8 v[216:219], v[192:193], v[146:147], v[216:219]
	v_mfma_f32_16x16x32_fp8_fp8 v[216:219], v[194:195], v[148:149], v[216:219]
	v_cndmask_b32_e64 v226, v204, v206, s[54:55]
	v_cndmask_b32_e64 v227, v205, v207, s[54:55]
	s_waitcnt vmcnt(16)
	ds_write_b128 v168, v[42:45]
	ds_write_b128 v168, v[46:49] offset:1024
	v_lshl_add_u32 v176, v160, 10, v166
	global_load_dwordx4 v[42:45], v176, s[50:51]
	v_lshl_add_u32 v177, v161, 10, v167
	global_load_dwordx4 v[46:49], v177, s[50:51]
	ds_read_b128 v[188:191], v169
	ds_read_b128 v[192:195], v170
	s_waitcnt lgkmcnt(4)
	v_mfma_f32_16x16x32_fp8_fp8 v[196:199], v[180:181], v[142:143], 0
	v_mfma_f32_16x16x32_fp8_fp8 v[196:199], v[182:183], v[144:145], v[196:199]
	v_mfma_f32_16x16x32_fp8_fp8 v[196:199], v[184:185], v[146:147], v[196:199]
	v_mfma_f32_16x16x32_fp8_fp8 v[196:199], v[186:187], v[148:149], v[196:199]
	v_cndmask_b32_e64 v228, v216, v218, s[54:55]
	v_cndmask_b32_e64 v229, v217, v219, s[54:55]
	v_cndmask_b32_e64 v232, v226, v228, s[56:57]
	v_cndmask_b32_e64 v233, v227, v229, s[56:57]
	s_waitcnt vmcnt(16)
	ds_write_b128 v168, v[50:53]
	ds_write_b128 v168, v[54:57] offset:1024
	v_lshl_add_u32 v174, v162, 10, v166
	global_load_dwordx4 v[50:53], v174, s[50:51]
	v_lshl_add_u32 v175, v163, 10, v167
	global_load_dwordx4 v[54:57], v175, s[50:51]
	ds_read_b128 v[180:183], v169
	ds_read_b128 v[184:187], v170
	s_waitcnt lgkmcnt(4)
	v_mfma_f32_16x16x32_fp8_fp8 v[200:203], v[188:189], v[142:143], 0
	v_mfma_f32_16x16x32_fp8_fp8 v[200:203], v[190:191], v[144:145], v[200:203]
	v_mfma_f32_16x16x32_fp8_fp8 v[200:203], v[192:193], v[146:147], v[200:203]
	v_mfma_f32_16x16x32_fp8_fp8 v[200:203], v[194:195], v[148:149], v[200:203]
	v_cndmask_b32_e64 v226, v196, v198, s[54:55]
	v_cndmask_b32_e64 v227, v197, v199, s[54:55]
	s_waitcnt vmcnt(16)
	ds_write_b128 v168, v[58:61]
	ds_write_b128 v168, v[62:65] offset:1024
	v_lshl_add_u32 v176, v164, 10, v166
	global_load_dwordx4 v[58:61], v176, s[50:51]
	v_lshl_add_u32 v177, v165, 10, v167
	global_load_dwordx4 v[62:65], v177, s[50:51]
	ds_read_b128 v[188:191], v169
	ds_read_b128 v[192:195], v170
	s_waitcnt lgkmcnt(4)
	v_mfma_f32_16x16x32_fp8_fp8 v[204:207], v[180:181], v[142:143], 0
	v_mfma_f32_16x16x32_fp8_fp8 v[204:207], v[182:183], v[144:145], v[204:207]
	v_mfma_f32_16x16x32_fp8_fp8 v[204:207], v[184:185], v[146:147], v[204:207]
	v_mfma_f32_16x16x32_fp8_fp8 v[204:207], v[186:187], v[148:149], v[204:207]
	v_cndmask_b32_e64 v228, v200, v202, s[54:55]
	v_cndmask_b32_e64 v229, v201, v203, s[54:55]
	v_cndmask_b32_e64 v234, v226, v228, s[56:57]
	v_cndmask_b32_e64 v235, v227, v229, s[56:57]
	s_waitcnt lgkmcnt(0)
	v_mfma_f32_16x16x32_fp8_fp8 v[216:219], v[188:189], v[142:143], 0
	v_mfma_f32_16x16x32_fp8_fp8 v[216:219], v[190:191], v[144:145], v[216:219]
	v_mfma_f32_16x16x32_fp8_fp8 v[216:219], v[192:193], v[146:147], v[216:219]
	v_mfma_f32_16x16x32_fp8_fp8 v[216:219], v[194:195], v[148:149], v[216:219]
	v_add_u32_e32 v0, 5632, v172
	ds_read2_b32 v[150:151], v0 offset0:0 offset1:8
	ds_read2_b32 v[152:153], v0 offset0:16 offset1:24
	ds_read2_b32 v[154:155], v0 offset0:32 offset1:40
	ds_read2_b32 v[156:157], v0 offset0:48 offset1:56
	ds_read2_b32 v[158:159], v0 offset0:64 offset1:72
	ds_read2_b32 v[160:161], v0 offset0:80 offset1:88
	ds_read2_b32 v[162:163], v0 offset0:96 offset1:104
	ds_read2_b32 v[164:165], v0 offset0:112 offset1:120
	v_add_u32_e32 v171, s80, v171
	global_load_dwordx4 v[142:145], v171, s[52:53]
	global_load_dwordx4 v[146:149], v171, s[52:53] offset:16
	v_cndmask_b32_e64 v226, v204, v206, s[54:55]
	v_cndmask_b32_e64 v227, v205, v207, s[54:55]
	v_cndmask_b32_e64 v228, v216, v218, s[54:55]
	v_cndmask_b32_e64 v229, v217, v219, s[54:55]
	v_cndmask_b32_e64 v236, v226, v228, s[56:57]
	v_cndmask_b32_e64 v237, v227, v229, s[56:57]
	v_cndmask_b32_e64 v226, v230, v232, s[58:59]
	v_cndmask_b32_e64 v228, v234, v236, s[58:59]
	v_cndmask_b32_e64 v227, v231, v233, s[58:59]
	v_cndmask_b32_e64 v229, v235, v237, s[58:59]
	v_cndmask_b32_e64 v226, v226, v228, s[60:61]
	v_cndmask_b32_e64 v227, v227, v229, s[60:61]
	v_add_f32_e32 v100, v100, v226
	v_add_f32_e32 v101, v101, v227
	s_waitcnt vmcnt(16)
	ds_write_b128 v168, v[2:5]
	ds_write_b128 v168, v[6:9] offset:1024
	s_waitcnt lgkmcnt(2)
	v_lshl_add_u32 v174, v150, 10, v166
	global_load_dwordx4 v[2:5], v174, s[50:51]
	v_lshl_add_u32 v175, v151, 10, v167
	global_load_dwordx4 v[6:9], v175, s[50:51]
	ds_read_b128 v[180:183], v169
	ds_read_b128 v[184:187], v170
	s_waitcnt vmcnt(16)
	ds_write_b128 v168, v[10:13]
	ds_write_b128 v168, v[14:17] offset:1024
	v_lshl_add_u32 v176, v152, 10, v166
	global_load_dwordx4 v[10:13], v176, s[50:51]
	v_lshl_add_u32 v177, v153, 10, v167
	global_load_dwordx4 v[14:17], v177, s[50:51]
	ds_read_b128 v[188:191], v169
	ds_read_b128 v[192:195], v170
	s_waitcnt lgkmcnt(4)
	v_mfma_f32_16x16x32_fp8_fp8 v[196:199], v[180:181], v[134:135], 0
	v_mfma_f32_16x16x32_fp8_fp8 v[196:199], v[182:183], v[136:137], v[196:199]
	v_mfma_f32_16x16x32_fp8_fp8 v[196:199], v[184:185], v[138:139], v[196:199]
	v_mfma_f32_16x16x32_fp8_fp8 v[196:199], v[186:187], v[140:141], v[196:199]
	s_waitcnt vmcnt(16)
	ds_write_b128 v168, v[18:21]
	ds_write_b128 v168, v[22:25] offset:1024
	v_lshl_add_u32 v174, v154, 10, v166
	global_load_dwordx4 v[18:21], v174, s[50:51]
	v_lshl_add_u32 v175, v155, 10, v167
	global_load_dwordx4 v[22:25], v175, s[50:51]
	ds_read_b128 v[180:183], v169
	ds_read_b128 v[184:187], v170
	s_waitcnt lgkmcnt(4)
	v_mfma_f32_16x16x32_fp8_fp8 v[200:203], v[188:189], v[134:135], 0
	v_mfma_f32_16x16x32_fp8_fp8 v[200:203], v[190:191], v[136:137], v[200:203]
	v_mfma_f32_16x16x32_fp8_fp8 v[200:203], v[192:193], v[138:139], v[200:203]
	v_mfma_f32_16x16x32_fp8_fp8 v[200:203], v[194:195], v[140:141], v[200:203]
	v_cndmask_b32_e64 v226, v196, v198, s[54:55]
	v_cndmask_b32_e64 v227, v197, v199, s[54:55]
	s_waitcnt vmcnt(16)
	ds_write_b128 v168, v[26:29]
	ds_write_b128 v168, v[30:33] offset:1024
	v_lshl_add_u32 v176, v156, 10, v166
	global_load_dwordx4 v[26:29], v176, s[50:51]
	v_lshl_add_u32 v177, v157, 10, v167
	global_load_dwordx4 v[30:33], v177, s[50:51]
	ds_read_b128 v[188:191], v169
	ds_read_b128 v[192:195], v170
	s_waitcnt lgkmcnt(4)
	v_mfma_f32_16x16x32_fp8_fp8 v[204:207], v[180:181], v[134:135], 0
	v_mfma_f32_16x16x32_fp8_fp8 v[204:207], v[182:183], v[136:137], v[204:207]
	v_mfma_f32_16x16x32_fp8_fp8 v[204:207], v[184:185], v[138:139], v[204:207]
	v_mfma_f32_16x16x32_fp8_fp8 v[204:207], v[186:187], v[140:141], v[204:207]
	v_cndmask_b32_e64 v228, v200, v202, s[54:55]
	v_cndmask_b32_e64 v229, v201, v203, s[54:55]
	v_cndmask_b32_e64 v230, v226, v228, s[56:57]
	v_cndmask_b32_e64 v231, v227, v229, s[56:57]
	s_waitcnt vmcnt(16)
	ds_write_b128 v168, v[34:37]
	ds_write_b128 v168, v[38:41] offset:1024
	v_lshl_add_u32 v174, v158, 10, v166
	global_load_dwordx4 v[34:37], v174, s[50:51]
	v_lshl_add_u32 v175, v159, 10, v167
	global_load_dwordx4 v[38:41], v175, s[50:51]
	ds_read_b128 v[180:183], v169
	ds_read_b128 v[184:187], v170
	s_waitcnt lgkmcnt(4)
	v_mfma_f32_16x16x32_fp8_fp8 v[216:219], v[188:189], v[134:135], 0
	v_mfma_f32_16x16x32_fp8_fp8 v[216:219], v[190:191], v[136:137], v[216:219]
	v_mfma_f32_16x16x32_fp8_fp8 v[216:219], v[192:193], v[138:139], v[216:219]
	v_mfma_f32_16x16x32_fp8_fp8 v[216:219], v[194:195], v[140:141], v[216:219]
	v_cndmask_b32_e64 v226, v204, v206, s[54:55]
	v_cndmask_b32_e64 v227, v205, v207, s[54:55]
	s_waitcnt vmcnt(16)
	ds_write_b128 v168, v[42:45]
	ds_write_b128 v168, v[46:49] offset:1024
	v_lshl_add_u32 v176, v160, 10, v166
	global_load_dwordx4 v[42:45], v176, s[50:51]
	v_lshl_add_u32 v177, v161, 10, v167
	global_load_dwordx4 v[46:49], v177, s[50:51]
	ds_read_b128 v[188:191], v169
	ds_read_b128 v[192:195], v170
	s_waitcnt lgkmcnt(4)
	v_mfma_f32_16x16x32_fp8_fp8 v[196:199], v[180:181], v[134:135], 0
	v_mfma_f32_16x16x32_fp8_fp8 v[196:199], v[182:183], v[136:137], v[196:199]
	v_mfma_f32_16x16x32_fp8_fp8 v[196:199], v[184:185], v[138:139], v[196:199]
	v_mfma_f32_16x16x32_fp8_fp8 v[196:199], v[186:187], v[140:141], v[196:199]
	v_cndmask_b32_e64 v228, v216, v218, s[54:55]
	v_cndmask_b32_e64 v229, v217, v219, s[54:55]
	v_cndmask_b32_e64 v232, v226, v228, s[56:57]
	v_cndmask_b32_e64 v233, v227, v229, s[56:57]
	s_waitcnt vmcnt(16)
	ds_write_b128 v168, v[50:53]
	ds_write_b128 v168, v[54:57] offset:1024
	v_lshl_add_u32 v174, v162, 10, v166
	global_load_dwordx4 v[50:53], v174, s[50:51]
	v_lshl_add_u32 v175, v163, 10, v167
	global_load_dwordx4 v[54:57], v175, s[50:51]
	ds_read_b128 v[180:183], v169
	ds_read_b128 v[184:187], v170
	s_waitcnt lgkmcnt(4)
	v_mfma_f32_16x16x32_fp8_fp8 v[200:203], v[188:189], v[134:135], 0
	v_mfma_f32_16x16x32_fp8_fp8 v[200:203], v[190:191], v[136:137], v[200:203]
	v_mfma_f32_16x16x32_fp8_fp8 v[200:203], v[192:193], v[138:139], v[200:203]
	v_mfma_f32_16x16x32_fp8_fp8 v[200:203], v[194:195], v[140:141], v[200:203]
	v_cndmask_b32_e64 v226, v196, v198, s[54:55]
	v_cndmask_b32_e64 v227, v197, v199, s[54:55]
	s_waitcnt vmcnt(16)
	ds_write_b128 v168, v[58:61]
	ds_write_b128 v168, v[62:65] offset:1024
	v_lshl_add_u32 v176, v164, 10, v166
	global_load_dwordx4 v[58:61], v176, s[50:51]
	v_lshl_add_u32 v177, v165, 10, v167
	global_load_dwordx4 v[62:65], v177, s[50:51]
	ds_read_b128 v[188:191], v169
	ds_read_b128 v[192:195], v170
	s_waitcnt lgkmcnt(4)
	v_mfma_f32_16x16x32_fp8_fp8 v[204:207], v[180:181], v[134:135], 0
	v_mfma_f32_16x16x32_fp8_fp8 v[204:207], v[182:183], v[136:137], v[204:207]
	v_mfma_f32_16x16x32_fp8_fp8 v[204:207], v[184:185], v[138:139], v[204:207]
	v_mfma_f32_16x16x32_fp8_fp8 v[204:207], v[186:187], v[140:141], v[204:207]
	v_cndmask_b32_e64 v228, v200, v202, s[54:55]
	v_cndmask_b32_e64 v229, v201, v203, s[54:55]
	v_cndmask_b32_e64 v234, v226, v228, s[56:57]
	v_cndmask_b32_e64 v235, v227, v229, s[56:57]
	s_waitcnt lgkmcnt(0)
	v_mfma_f32_16x16x32_fp8_fp8 v[216:219], v[188:189], v[134:135], 0
	v_mfma_f32_16x16x32_fp8_fp8 v[216:219], v[190:191], v[136:137], v[216:219]
	v_mfma_f32_16x16x32_fp8_fp8 v[216:219], v[192:193], v[138:139], v[216:219]
	v_mfma_f32_16x16x32_fp8_fp8 v[216:219], v[194:195], v[140:141], v[216:219]
	v_add_u32_e32 v0, 0, v172
	ds_read2_b32 v[150:151], v0 offset0:0 offset1:8
	ds_read2_b32 v[152:153], v0 offset0:16 offset1:24
	ds_read2_b32 v[154:155], v0 offset0:32 offset1:40
	ds_read2_b32 v[156:157], v0 offset0:48 offset1:56
	ds_read2_b32 v[158:159], v0 offset0:64 offset1:72
	ds_read2_b32 v[160:161], v0 offset0:80 offset1:88
	ds_read2_b32 v[162:163], v0 offset0:96 offset1:104
	ds_read2_b32 v[164:165], v0 offset0:112 offset1:120
	v_add_u32_e32 v171, s81, v171
	global_load_dwordx4 v[134:137], v171, s[52:53]
	global_load_dwordx4 v[138:141], v171, s[52:53] offset:16
	v_cndmask_b32_e64 v226, v204, v206, s[54:55]
	v_cndmask_b32_e64 v227, v205, v207, s[54:55]
	v_cndmask_b32_e64 v228, v216, v218, s[54:55]
	v_cndmask_b32_e64 v229, v217, v219, s[54:55]
	v_cndmask_b32_e64 v236, v226, v228, s[56:57]
	v_cndmask_b32_e64 v237, v227, v229, s[56:57]
	v_cndmask_b32_e64 v226, v230, v232, s[58:59]
	v_cndmask_b32_e64 v228, v234, v236, s[58:59]
	v_cndmask_b32_e64 v227, v231, v233, s[58:59]
	v_cndmask_b32_e64 v229, v235, v237, s[58:59]
	v_cndmask_b32_e64 v226, v226, v228, s[60:61]
	v_cndmask_b32_e64 v227, v227, v229, s[60:61]
	v_add_f32_e32 v66, v66, v226
	v_add_f32_e32 v67, v67, v227
	v_add_u32_e32 v166, 0x80, v166
	v_add_u32_e32 v167, 0x80, v167
	s_waitcnt vmcnt(16)
	ds_write_b128 v168, v[2:5]
	ds_write_b128 v168, v[6:9] offset:1024
	s_waitcnt lgkmcnt(2)
	v_lshl_add_u32 v174, v150, 10, v166
	global_load_dwordx4 v[2:5], v174, s[50:51]
	v_lshl_add_u32 v175, v151, 10, v167
	global_load_dwordx4 v[6:9], v175, s[50:51]
	ds_read_b128 v[180:183], v169
	ds_read_b128 v[184:187], v170
	s_waitcnt vmcnt(16)
	ds_write_b128 v168, v[10:13]
	ds_write_b128 v168, v[14:17] offset:1024
	v_lshl_add_u32 v176, v152, 10, v166
	global_load_dwordx4 v[10:13], v176, s[50:51]
	v_lshl_add_u32 v177, v153, 10, v167
	global_load_dwordx4 v[14:17], v177, s[50:51]
	ds_read_b128 v[188:191], v169
	ds_read_b128 v[192:195], v170
	s_waitcnt lgkmcnt(4)
	v_mfma_f32_16x16x32_fp8_fp8 v[196:199], v[180:181], v[142:143], 0
	v_mfma_f32_16x16x32_fp8_fp8 v[196:199], v[182:183], v[144:145], v[196:199]
	v_mfma_f32_16x16x32_fp8_fp8 v[196:199], v[184:185], v[146:147], v[196:199]
	v_mfma_f32_16x16x32_fp8_fp8 v[196:199], v[186:187], v[148:149], v[196:199]
	s_waitcnt vmcnt(16)
	ds_write_b128 v168, v[18:21]
	ds_write_b128 v168, v[22:25] offset:1024
	v_lshl_add_u32 v174, v154, 10, v166
	global_load_dwordx4 v[18:21], v174, s[50:51]
	v_lshl_add_u32 v175, v155, 10, v167
	global_load_dwordx4 v[22:25], v175, s[50:51]
	ds_read_b128 v[180:183], v169
	ds_read_b128 v[184:187], v170
	s_waitcnt lgkmcnt(4)
	v_mfma_f32_16x16x32_fp8_fp8 v[200:203], v[188:189], v[142:143], 0
	v_mfma_f32_16x16x32_fp8_fp8 v[200:203], v[190:191], v[144:145], v[200:203]
	v_mfma_f32_16x16x32_fp8_fp8 v[200:203], v[192:193], v[146:147], v[200:203]
	v_mfma_f32_16x16x32_fp8_fp8 v[200:203], v[194:195], v[148:149], v[200:203]
	v_cndmask_b32_e64 v226, v196, v198, s[54:55]
	v_cndmask_b32_e64 v227, v197, v199, s[54:55]
	s_waitcnt vmcnt(16)
	ds_write_b128 v168, v[26:29]
	ds_write_b128 v168, v[30:33] offset:1024
	v_lshl_add_u32 v176, v156, 10, v166
	global_load_dwordx4 v[26:29], v176, s[50:51]
	v_lshl_add_u32 v177, v157, 10, v167
	global_load_dwordx4 v[30:33], v177, s[50:51]
	ds_read_b128 v[188:191], v169
	ds_read_b128 v[192:195], v170
	s_waitcnt lgkmcnt(4)
	v_mfma_f32_16x16x32_fp8_fp8 v[204:207], v[180:181], v[142:143], 0
	v_mfma_f32_16x16x32_fp8_fp8 v[204:207], v[182:183], v[144:145], v[204:207]
	v_mfma_f32_16x16x32_fp8_fp8 v[204:207], v[184:185], v[146:147], v[204:207]
	v_mfma_f32_16x16x32_fp8_fp8 v[204:207], v[186:187], v[148:149], v[204:207]
	v_cndmask_b32_e64 v228, v200, v202, s[54:55]
	v_cndmask_b32_e64 v229, v201, v203, s[54:55]
	v_cndmask_b32_e64 v230, v226, v228, s[56:57]
	v_cndmask_b32_e64 v231, v227, v229, s[56:57]
	s_waitcnt vmcnt(16)
	ds_write_b128 v168, v[34:37]
	ds_write_b128 v168, v[38:41] offset:1024
	v_lshl_add_u32 v174, v158, 10, v166
	global_load_dwordx4 v[34:37], v174, s[50:51]
	v_lshl_add_u32 v175, v159, 10, v167
	global_load_dwordx4 v[38:41], v175, s[50:51]
	ds_read_b128 v[180:183], v169
	ds_read_b128 v[184:187], v170
	s_waitcnt lgkmcnt(4)
	v_mfma_f32_16x16x32_fp8_fp8 v[216:219], v[188:189], v[142:143], 0
	v_mfma_f32_16x16x32_fp8_fp8 v[216:219], v[190:191], v[144:145], v[216:219]
	v_mfma_f32_16x16x32_fp8_fp8 v[216:219], v[192:193], v[146:147], v[216:219]
	v_mfma_f32_16x16x32_fp8_fp8 v[216:219], v[194:195], v[148:149], v[216:219]
	v_cndmask_b32_e64 v226, v204, v206, s[54:55]
	v_cndmask_b32_e64 v227, v205, v207, s[54:55]
	s_waitcnt vmcnt(16)
	ds_write_b128 v168, v[42:45]
	ds_write_b128 v168, v[46:49] offset:1024
	v_lshl_add_u32 v176, v160, 10, v166
	global_load_dwordx4 v[42:45], v176, s[50:51]
	v_lshl_add_u32 v177, v161, 10, v167
	global_load_dwordx4 v[46:49], v177, s[50:51]
	ds_read_b128 v[188:191], v169
	ds_read_b128 v[192:195], v170
	s_waitcnt lgkmcnt(4)
	v_mfma_f32_16x16x32_fp8_fp8 v[196:199], v[180:181], v[142:143], 0
	v_mfma_f32_16x16x32_fp8_fp8 v[196:199], v[182:183], v[144:145], v[196:199]
	v_mfma_f32_16x16x32_fp8_fp8 v[196:199], v[184:185], v[146:147], v[196:199]
	v_mfma_f32_16x16x32_fp8_fp8 v[196:199], v[186:187], v[148:149], v[196:199]
	v_cndmask_b32_e64 v228, v216, v218, s[54:55]
	v_cndmask_b32_e64 v229, v217, v219, s[54:55]
	v_cndmask_b32_e64 v232, v226, v228, s[56:57]
	v_cndmask_b32_e64 v233, v227, v229, s[56:57]
	s_waitcnt vmcnt(16)
	ds_write_b128 v168, v[50:53]
	ds_write_b128 v168, v[54:57] offset:1024
	v_lshl_add_u32 v174, v162, 10, v166
	global_load_dwordx4 v[50:53], v174, s[50:51]
	v_lshl_add_u32 v175, v163, 10, v167
	global_load_dwordx4 v[54:57], v175, s[50:51]
	ds_read_b128 v[180:183], v169
	ds_read_b128 v[184:187], v170
	s_waitcnt lgkmcnt(4)
	v_mfma_f32_16x16x32_fp8_fp8 v[200:203], v[188:189], v[142:143], 0
	v_mfma_f32_16x16x32_fp8_fp8 v[200:203], v[190:191], v[144:145], v[200:203]
	v_mfma_f32_16x16x32_fp8_fp8 v[200:203], v[192:193], v[146:147], v[200:203]
	v_mfma_f32_16x16x32_fp8_fp8 v[200:203], v[194:195], v[148:149], v[200:203]
	v_cndmask_b32_e64 v226, v196, v198, s[54:55]
	v_cndmask_b32_e64 v227, v197, v199, s[54:55]
	s_waitcnt vmcnt(16)
	ds_write_b128 v168, v[58:61]
	ds_write_b128 v168, v[62:65] offset:1024
	v_lshl_add_u32 v176, v164, 10, v166
	global_load_dwordx4 v[58:61], v176, s[50:51]
	v_lshl_add_u32 v177, v165, 10, v167
	global_load_dwordx4 v[62:65], v177, s[50:51]
	ds_read_b128 v[188:191], v169
	ds_read_b128 v[192:195], v170
	s_waitcnt lgkmcnt(4)
	v_mfma_f32_16x16x32_fp8_fp8 v[204:207], v[180:181], v[142:143], 0
	v_mfma_f32_16x16x32_fp8_fp8 v[204:207], v[182:183], v[144:145], v[204:207]
	v_mfma_f32_16x16x32_fp8_fp8 v[204:207], v[184:185], v[146:147], v[204:207]
	v_mfma_f32_16x16x32_fp8_fp8 v[204:207], v[186:187], v[148:149], v[204:207]
	v_cndmask_b32_e64 v228, v200, v202, s[54:55]
	v_cndmask_b32_e64 v229, v201, v203, s[54:55]
	v_cndmask_b32_e64 v234, v226, v228, s[56:57]
	v_cndmask_b32_e64 v235, v227, v229, s[56:57]
	s_waitcnt lgkmcnt(0)
	v_mfma_f32_16x16x32_fp8_fp8 v[216:219], v[188:189], v[142:143], 0
	v_mfma_f32_16x16x32_fp8_fp8 v[216:219], v[190:191], v[144:145], v[216:219]
	v_mfma_f32_16x16x32_fp8_fp8 v[216:219], v[192:193], v[146:147], v[216:219]
	v_mfma_f32_16x16x32_fp8_fp8 v[216:219], v[194:195], v[148:149], v[216:219]
	v_add_u32_e32 v0, 512, v172
	ds_read2_b32 v[150:151], v0 offset0:0 offset1:8
	ds_read2_b32 v[152:153], v0 offset0:16 offset1:24
	ds_read2_b32 v[154:155], v0 offset0:32 offset1:40
	ds_read2_b32 v[156:157], v0 offset0:48 offset1:56
	ds_read2_b32 v[158:159], v0 offset0:64 offset1:72
	ds_read2_b32 v[160:161], v0 offset0:80 offset1:88
	ds_read2_b32 v[162:163], v0 offset0:96 offset1:104
	ds_read2_b32 v[164:165], v0 offset0:112 offset1:120
	v_add_u32_e32 v171, s80, v171
	global_load_dwordx4 v[142:145], v171, s[52:53]
	global_load_dwordx4 v[146:149], v171, s[52:53] offset:16
	v_cndmask_b32_e64 v226, v204, v206, s[54:55]
	v_cndmask_b32_e64 v227, v205, v207, s[54:55]
	v_cndmask_b32_e64 v228, v216, v218, s[54:55]
	v_cndmask_b32_e64 v229, v217, v219, s[54:55]
	v_cndmask_b32_e64 v236, v226, v228, s[56:57]
	v_cndmask_b32_e64 v237, v227, v229, s[56:57]
	v_cndmask_b32_e64 v226, v230, v232, s[58:59]
	v_cndmask_b32_e64 v228, v234, v236, s[58:59]
	v_cndmask_b32_e64 v227, v231, v233, s[58:59]
	v_cndmask_b32_e64 v229, v235, v237, s[58:59]
	v_cndmask_b32_e64 v226, v226, v228, s[60:61]
	v_cndmask_b32_e64 v227, v227, v229, s[60:61]
	v_add_f32_e32 v68, v68, v226
	v_add_f32_e32 v69, v69, v227
	s_add_i32 s49, s49, 1
	s_cmp_lt_u32 s49, 8
	s_cbranch_scc1 .Lu_cloop
	s_waitcnt vmcnt(0)
	ds_write_b64 v173, v[242:243] offset:0
	ds_write_b64 v173, v[244:245] offset:512
	ds_write_b64 v173, v[246:247] offset:1024
	ds_write_b64 v173, v[248:249] offset:1536
	ds_write_b64 v173, v[238:239] offset:2048
	ds_write_b64 v173, v[240:241] offset:2560
	ds_write_b64 v173, v[94:95] offset:3072
	ds_write_b64 v173, v[96:97] offset:3584
	ds_write_b64 v173, v[98:99] offset:4096
	ds_write_b64 v173, v[100:101] offset:4608
	ds_write_b64 v173, v[66:67] offset:5120
	ds_write_b64 v173, v[68:69] offset:5632
	s_branch .LBB0_2015
